# ret_intra epilogue: bf16 cross/gate/output accessed as dwords with neighbour-lane swap (VMEM ops per row 48 -> 24)
# baseline (speedup 1.0000x reference)
.LBB0_678:
	s_addk_i32 s95, 0x4000
	v_lshl_add_u64 v[90:91], v[90:91], 0, s[76:77]
	v_lshl_add_u64 v[92:93], v[92:93], 0, s[76:77]
	v_lshl_add_u64 v[94:95], v[94:95], 0, s[76:77]
	v_lshl_add_u64 v[96:97], v[96:97], 0, s[76:77]
	v_lshl_add_u64 v[98:99], v[98:99], 0, s[76:77]
	v_lshl_add_u64 v[100:101], v[100:101], 0, s[76:77]
	v_lshl_add_u64 v[102:103], v[102:103], 0, s[76:77]
	v_lshl_add_u64 v[104:105], v[104:105], 0, s[76:77]
	s_lshl_b32 s96, s9, 1
	v_mov_b32_e32 v111, v71
	v_and_b32_e32 v246, 1, v152
	v_sub_u32_e32 v240, 0, v246
	v_mul_u32_u24_e32 v244, 30, v246
	v_mov_b32_e32 v245, 0
	v_mov_b32_e32 v247, 0x7060c0c
	v_mov_b32_e32 v248, 0x1000c0c
	v_bfi_b32 v241, v240, v247, v248
	v_mov_b32_e32 v247, 0x3020c0c
	v_mov_b32_e32 v248, 0x5040c0c
	v_bfi_b32 v242, v240, v247, v248
	v_mov_b32_e32 v247, 0x3020706
	v_mov_b32_e32 v248, 0x7060302
	v_bfi_b32 v243, v240, v247, v248
	s_lshl_b32 s0, s9, 2
	s_mov_b32 s1, s97
	v_lshl_add_u64 v[120:121], v[88:89], 0, s[0:1]
	global_load_dword v182, v[120:121], off offset:0
	global_load_dword v183, v[120:121], off offset:64
	global_load_dword v184, v[120:121], off offset:128
	global_load_dword v185, v[120:121], off offset:192
	global_load_dword v186, v[120:121], off offset:256
	global_load_dword v187, v[120:121], off offset:320
	global_load_dword v188, v[120:121], off offset:384
	global_load_dword v189, v[120:121], off offset:448
	global_load_dword v190, v[120:121], off offset:512
	global_load_dword v191, v[120:121], off offset:576
	global_load_dword v192, v[120:121], off offset:640
	global_load_dword v193, v[120:121], off offset:704
	global_load_dword v194, v[120:121], off offset:768
	global_load_dword v195, v[120:121], off offset:832
	global_load_dword v196, v[120:121], off offset:896
	global_load_dword v197, v[120:121], off offset:960
	v_mov_b32_e32 v113, s11
	v_or_b32_e32 v112, s10, v86
	v_lshlrev_b64 v[114:115], 12, v[112:113]
	v_lshl_add_u64 v[114:115], s[78:79], 0, v[114:115]
	v_lshl_add_u64 v[114:115], v[114:115], 0, s[96:97]
	v_lshl_add_u64 v[114:115], v[114:115], 0, v[110:111]
	v_lshl_add_u64 v[114:115], v[114:115], 0, s[80:81]
	v_lshlrev_b64 v[118:119], 13, v[112:113]
	v_lshl_add_u64 v[118:119], s[92:93], 0, v[118:119]
	v_lshl_add_u64 v[118:119], v[118:119], 0, s[96:97]
	v_lshl_add_u64 v[118:119], v[118:119], 0, v[110:111]
	v_lshl_add_u64 v[118:119], v[118:119], 0, s[90:91]
	v_lshl_add_u64 v[114:115], v[114:115], 0, v[244:245]
	v_lshl_add_u64 v[118:119], v[118:119], 0, v[244:245]
	global_load_dword v198, v[114:115], off offset:0
	global_load_dword v199, v[114:115], off offset:64
	global_load_dword v200, v[114:115], off offset:128
	global_load_dword v201, v[114:115], off offset:192
	global_load_dword v202, v[114:115], off offset:256
	global_load_dword v203, v[114:115], off offset:320
	global_load_dword v204, v[114:115], off offset:384
	global_load_dword v205, v[114:115], off offset:448
	global_load_dword v214, v[118:119], off offset:0
	global_load_dword v215, v[118:119], off offset:64
	global_load_dword v216, v[118:119], off offset:128
	global_load_dword v217, v[118:119], off offset:192
	global_load_dword v218, v[118:119], off offset:256
	global_load_dword v219, v[118:119], off offset:320
	global_load_dword v220, v[118:119], off offset:384
	global_load_dword v221, v[118:119], off offset:448
	v_mov_b32_e32 v120, v114
	v_mov_b32_e32 v121, v115
	s_waitcnt vmcnt(8)
	v_mov_b32_dpp v206, v198 quad_perm:[1,0,3,2] row_mask:0xf bank_mask:0xf
	v_mov_b32_dpp v207, v199 quad_perm:[1,0,3,2] row_mask:0xf bank_mask:0xf
	v_mov_b32_dpp v208, v200 quad_perm:[1,0,3,2] row_mask:0xf bank_mask:0xf
	v_mov_b32_dpp v209, v201 quad_perm:[1,0,3,2] row_mask:0xf bank_mask:0xf
	v_mov_b32_dpp v210, v202 quad_perm:[1,0,3,2] row_mask:0xf bank_mask:0xf
	v_mov_b32_dpp v211, v203 quad_perm:[1,0,3,2] row_mask:0xf bank_mask:0xf
	v_mov_b32_dpp v212, v204 quad_perm:[1,0,3,2] row_mask:0xf bank_mask:0xf
	v_mov_b32_dpp v213, v205 quad_perm:[1,0,3,2] row_mask:0xf bank_mask:0xf
	v_perm_b32 v231, v206, v198, v241
	v_add_f32_e32 v62, v62, v231
	v_add_f32_e32 v230, 0, v62
	v_perm_b32 v233, v206, v198, v242
	v_add_f32_e32 v58, v58, v233
	v_add_f32_e32 v230, v230, v58
	v_perm_b32 v231, v207, v199, v241
	v_add_f32_e32 v54, v54, v231
	v_add_f32_e32 v230, v230, v54
	v_perm_b32 v233, v207, v199, v242
	v_add_f32_e32 v50, v50, v233
	v_add_f32_e32 v230, v230, v50
	v_perm_b32 v231, v208, v200, v241
	v_add_f32_e32 v46, v46, v231
	v_add_f32_e32 v230, v230, v46
	v_perm_b32 v233, v208, v200, v242
	v_add_f32_e32 v42, v42, v233
	v_add_f32_e32 v230, v230, v42
	v_perm_b32 v231, v209, v201, v241
	v_add_f32_e32 v38, v38, v231
	v_add_f32_e32 v230, v230, v38
	v_perm_b32 v233, v209, v201, v242
	v_add_f32_e32 v34, v34, v233
	v_add_f32_e32 v230, v230, v34
	v_perm_b32 v231, v210, v202, v241
	v_add_f32_e32 v30, v30, v231
	v_add_f32_e32 v230, v230, v30
	v_perm_b32 v233, v210, v202, v242
	v_add_f32_e32 v26, v26, v233
	v_add_f32_e32 v230, v230, v26
	v_perm_b32 v231, v211, v203, v241
	v_add_f32_e32 v22, v22, v231
	v_add_f32_e32 v230, v230, v22
	v_perm_b32 v233, v211, v203, v242
	v_add_f32_e32 v18, v18, v233
	v_add_f32_e32 v230, v230, v18
	v_perm_b32 v231, v212, v204, v241
	v_add_f32_e32 v14, v14, v231
	v_add_f32_e32 v230, v230, v14
	v_perm_b32 v233, v212, v204, v242
	v_add_f32_e32 v10, v10, v233
	v_add_f32_e32 v230, v230, v10
	v_perm_b32 v231, v213, v205, v241
	v_add_f32_e32 v6, v6, v231
	v_add_f32_e32 v230, v230, v6
	v_perm_b32 v233, v213, v205, v242
	v_add_f32_e32 v2, v2, v233
	v_add_f32_e32 v230, v230, v2
	v_or_b32_e32 v116, 1, v112
	v_mov_b32_e32 v117, s11
	v_lshlrev_b64 v[114:115], 12, v[116:117]
	v_lshl_add_u64 v[114:115], s[78:79], 0, v[114:115]
	v_lshl_add_u64 v[114:115], v[114:115], 0, s[96:97]
	v_lshl_add_u64 v[114:115], v[114:115], 0, v[110:111]
	v_lshl_add_u64 v[114:115], v[114:115], 0, s[80:81]
	v_lshlrev_b64 v[118:119], 13, v[116:117]
	v_lshl_add_u64 v[118:119], s[92:93], 0, v[118:119]
	v_lshl_add_u64 v[118:119], v[118:119], 0, s[96:97]
	v_lshl_add_u64 v[118:119], v[118:119], 0, v[110:111]
	v_lshl_add_u64 v[118:119], v[118:119], 0, s[90:91]
	v_lshl_add_u64 v[114:115], v[114:115], 0, v[244:245]
	v_lshl_add_u64 v[118:119], v[118:119], 0, v[244:245]
	global_load_dword v198, v[114:115], off offset:0
	global_load_dword v199, v[114:115], off offset:64
	global_load_dword v200, v[114:115], off offset:128
	global_load_dword v201, v[114:115], off offset:192
	global_load_dword v202, v[114:115], off offset:256
	global_load_dword v203, v[114:115], off offset:320
	global_load_dword v204, v[114:115], off offset:384
	global_load_dword v205, v[114:115], off offset:448
	s_nop 1
	v_add_f32_dpp v230, v230, v230 row_ror:8 row_mask:0xf bank_mask:0xf bound_ctrl:1
	s_nop 1
	v_add_f32_dpp v230, v230, v230 row_ror:4 row_mask:0xf bank_mask:0xf bound_ctrl:1
	s_nop 1
	v_add_f32_dpp v230, v230, v230 row_ror:2 row_mask:0xf bank_mask:0xf bound_ctrl:1
	s_nop 1
	v_add_f32_dpp v230, v230, v230 row_ror:1 row_mask:0xf bank_mask:0xf bound_ctrl:1
	v_fmac_f32_e32 v58, 0xbb800000, v230
	v_mul_f32_e32 v231, v58, v58
	v_fmac_f32_e32 v62, 0xbb800000, v230
	v_fmac_f32_e32 v231, v62, v62
	v_fmac_f32_e32 v54, 0xbb800000, v230
	v_fmac_f32_e32 v231, v54, v54
	v_fmac_f32_e32 v50, 0xbb800000, v230
	v_fmac_f32_e32 v231, v50, v50
	v_fmac_f32_e32 v46, 0xbb800000, v230
	v_fmac_f32_e32 v231, v46, v46
	v_fmac_f32_e32 v42, 0xbb800000, v230
	v_fmac_f32_e32 v231, v42, v42
	v_fmac_f32_e32 v38, 0xbb800000, v230
	v_fmac_f32_e32 v231, v38, v38
	v_fmac_f32_e32 v34, 0xbb800000, v230
	v_fmac_f32_e32 v231, v34, v34
	v_fmac_f32_e32 v30, 0xbb800000, v230
	v_fmac_f32_e32 v231, v30, v30
	v_fmac_f32_e32 v26, 0xbb800000, v230
	v_fmac_f32_e32 v231, v26, v26
	v_fmac_f32_e32 v22, 0xbb800000, v230
	v_fmac_f32_e32 v231, v22, v22
	v_fmac_f32_e32 v18, 0xbb800000, v230
	v_fmac_f32_e32 v231, v18, v18
	v_fmac_f32_e32 v14, 0xbb800000, v230
	v_fmac_f32_e32 v231, v14, v14
	v_fmac_f32_e32 v10, 0xbb800000, v230
	v_fmac_f32_e32 v231, v10, v10
	v_fmac_f32_e32 v6, 0xbb800000, v230
	v_fmac_f32_e32 v231, v6, v6
	v_fmac_f32_e32 v2, 0xbb800000, v230
	v_fmac_f32_e32 v231, v2, v2
	s_nop 1
	v_add_f32_dpp v232, v231, v231 row_ror:8 row_mask:0xf bank_mask:0xf bound_ctrl:1
	s_nop 1
	v_add_f32_dpp v232, v232, v232 row_ror:4 row_mask:0xf bank_mask:0xf bound_ctrl:1
	s_nop 1
	v_add_f32_dpp v232, v232, v232 row_ror:2 row_mask:0xf bank_mask:0xf bound_ctrl:1
	s_nop 1
	v_add_f32_dpp v232, v232, v232 row_ror:1 row_mask:0xf bank_mask:0xf bound_ctrl:1
	v_fmamk_f32 v232, v232, 0x3b800000, v169
	v_cmp_gt_f32_e32 vcc, s7, v232
	v_mul_f32_e32 v233, 0x4f800000, v232
	s_nop 0
	v_cndmask_b32_e32 v232, v232, v233, vcc
	v_sqrt_f32_e32 v233, v232
	s_nop 0
	v_add_u32_e32 v234, -1, v233
	v_fma_f32 v235, -v234, v233, v232
	v_cmp_ge_f32_e64 s[0:1], 0, v235
	v_add_u32_e32 v235, 1, v233
	s_nop 0
	v_cndmask_b32_e64 v234, v233, v234, s[0:1]
	v_fma_f32 v233, -v235, v233, v232
	v_cmp_lt_f32_e64 s[0:1], 0, v233
	s_nop 1
	v_cndmask_b32_e64 v233, v234, v235, s[0:1]
	v_mul_f32_e32 v234, 0x37800000, v233
	s_nop 0
	v_cndmask_b32_e32 v233, v233, v234, vcc
	v_cmp_class_f32_e32 vcc, v232, v170
	s_nop 1
	v_cndmask_b32_e32 v232, v233, v232, vcc
	v_div_scale_f32 v233, s[0:1], v232, v232, 1.0
	v_rcp_f32_e32 v234, v233
	s_nop 0
	v_fma_f32 v235, -v233, v234, 1.0
	v_fmac_f32_e32 v234, v235, v234
	v_div_scale_f32 v235, vcc, 1.0, v232, 1.0
	v_mul_f32_e32 v236, v235, v234
	v_fma_f32 v237, -v233, v236, v235
	v_fmac_f32_e32 v236, v237, v234
	v_fma_f32 v233, -v233, v236, v235
	v_div_fmas_f32 v233, v233, v234, v236
	v_div_fixup_f32 v232, v233, v232, 1.0
	s_waitcnt vmcnt(8)
	v_mov_b32_dpp v222, v214 quad_perm:[1,0,3,2] row_mask:0xf bank_mask:0xf
	v_mov_b32_dpp v223, v215 quad_perm:[1,0,3,2] row_mask:0xf bank_mask:0xf
	v_mov_b32_dpp v224, v216 quad_perm:[1,0,3,2] row_mask:0xf bank_mask:0xf
	v_mov_b32_dpp v225, v217 quad_perm:[1,0,3,2] row_mask:0xf bank_mask:0xf
	v_mov_b32_dpp v226, v218 quad_perm:[1,0,3,2] row_mask:0xf bank_mask:0xf
	v_mov_b32_dpp v227, v219 quad_perm:[1,0,3,2] row_mask:0xf bank_mask:0xf
	v_mov_b32_dpp v228, v220 quad_perm:[1,0,3,2] row_mask:0xf bank_mask:0xf
	v_mov_b32_dpp v229, v221 quad_perm:[1,0,3,2] row_mask:0xf bank_mask:0xf
	v_perm_b32 v174, v222, v214, v241
	v_mul_f32_e32 v175, 0xbfb8aa3b, v174
	v_exp_f32_e32 v175, v175
	v_mul_f32_e32 v176, v62, v232
	v_mul_f32_e32 v176, v182, v176
	v_add_f32_e32 v175, 1.0, v175
	v_div_scale_f32 v177, s[0:1], v175, v175, 1.0
	v_rcp_f32_e32 v178, v177
	s_nop 0
	v_fma_f32 v179, -v177, v178, 1.0
	v_fmac_f32_e32 v178, v179, v178
	v_div_scale_f32 v179, vcc, 1.0, v175, 1.0
	v_mul_f32_e32 v180, v179, v178
	v_fma_f32 v181, -v177, v180, v179
	v_fmac_f32_e32 v180, v181, v178
	v_fma_f32 v177, -v177, v180, v179
	v_div_fmas_f32 v177, v177, v178, v180
	v_div_fixup_f32 v175, v177, v175, 1.0
	v_mul_f32_e32 v174, v175, v174
	v_mul_f32_e32 v174, v174, v176
	v_bfe_u32 v176, v174, 16, 1
	v_add3_u32 v174, v174, v176, s5
	v_perm_b32 v230, v222, v214, v242
	v_mul_f32_e32 v231, 0xbfb8aa3b, v230
	v_exp_f32_e32 v231, v231
	v_mul_f32_e32 v233, v58, v232
	v_mul_f32_e32 v233, v183, v233
	v_add_f32_e32 v231, 1.0, v231
	v_div_scale_f32 v234, s[0:1], v231, v231, 1.0
	v_rcp_f32_e32 v235, v234
	s_nop 0
	v_fma_f32 v236, -v234, v235, 1.0
	v_fmac_f32_e32 v235, v236, v235
	v_div_scale_f32 v236, vcc, 1.0, v231, 1.0
	v_mul_f32_e32 v237, v236, v235
	v_fma_f32 v109, -v234, v237, v236
	v_fmac_f32_e32 v237, v109, v235
	v_fma_f32 v234, -v234, v237, v236
	v_div_fmas_f32 v234, v234, v235, v237
	v_div_fixup_f32 v231, v234, v231, 1.0
	v_mul_f32_e32 v230, v231, v230
	v_mul_f32_e32 v230, v230, v233
	v_bfe_u32 v233, v230, 16, 1
	v_add3_u32 v230, v230, v233, s5
	v_bfi_b32 v246, v240, v174, v230
	v_bfi_b32 v248, v240, v230, v174
	s_nop 0
	v_mov_b32_dpp v247, v246 quad_perm:[1,0,3,2] row_mask:0xf bank_mask:0xf
	s_nop 0
	v_perm_b32 v248, v247, v248, v243
	global_store_dword v[120:121], v248, off offset:0
	v_perm_b32 v174, v223, v215, v241
	v_mul_f32_e32 v175, 0xbfb8aa3b, v174
	v_exp_f32_e32 v175, v175
	v_mul_f32_e32 v176, v54, v232
	v_mul_f32_e32 v176, v184, v176
	v_add_f32_e32 v175, 1.0, v175
	v_div_scale_f32 v177, s[0:1], v175, v175, 1.0
	v_rcp_f32_e32 v178, v177
	s_nop 0
	v_fma_f32 v179, -v177, v178, 1.0
	v_fmac_f32_e32 v178, v179, v178
	v_div_scale_f32 v179, vcc, 1.0, v175, 1.0
	v_mul_f32_e32 v180, v179, v178
	v_fma_f32 v181, -v177, v180, v179
	v_fmac_f32_e32 v180, v181, v178
	v_fma_f32 v177, -v177, v180, v179
	v_div_fmas_f32 v177, v177, v178, v180
	v_div_fixup_f32 v175, v177, v175, 1.0
	v_mul_f32_e32 v174, v175, v174
	v_mul_f32_e32 v174, v174, v176
	v_bfe_u32 v176, v174, 16, 1
	v_add3_u32 v174, v174, v176, s5
	v_perm_b32 v230, v223, v215, v242
	v_mul_f32_e32 v231, 0xbfb8aa3b, v230
	v_exp_f32_e32 v231, v231
	v_mul_f32_e32 v233, v50, v232
	v_mul_f32_e32 v233, v185, v233
	v_add_f32_e32 v231, 1.0, v231
	v_div_scale_f32 v234, s[0:1], v231, v231, 1.0
	v_rcp_f32_e32 v235, v234
	s_nop 0
	v_fma_f32 v236, -v234, v235, 1.0
	v_fmac_f32_e32 v235, v236, v235
	v_div_scale_f32 v236, vcc, 1.0, v231, 1.0
	v_mul_f32_e32 v237, v236, v235
	v_fma_f32 v109, -v234, v237, v236
	v_fmac_f32_e32 v237, v109, v235
	v_fma_f32 v234, -v234, v237, v236
	v_div_fmas_f32 v234, v234, v235, v237
	v_div_fixup_f32 v231, v234, v231, 1.0
	v_mul_f32_e32 v230, v231, v230
	v_mul_f32_e32 v230, v230, v233
	v_bfe_u32 v233, v230, 16, 1
	v_add3_u32 v230, v230, v233, s5
	v_bfi_b32 v246, v240, v174, v230
	v_bfi_b32 v248, v240, v230, v174
	s_nop 0
	v_mov_b32_dpp v247, v246 quad_perm:[1,0,3,2] row_mask:0xf bank_mask:0xf
	s_nop 0
	v_perm_b32 v248, v247, v248, v243
	global_store_dword v[120:121], v248, off offset:64
	v_perm_b32 v174, v224, v216, v241
	v_mul_f32_e32 v175, 0xbfb8aa3b, v174
	v_exp_f32_e32 v175, v175
	v_mul_f32_e32 v176, v46, v232
	v_mul_f32_e32 v176, v186, v176
	v_add_f32_e32 v175, 1.0, v175
	v_div_scale_f32 v177, s[0:1], v175, v175, 1.0
	v_rcp_f32_e32 v178, v177
	s_nop 0
	v_fma_f32 v179, -v177, v178, 1.0
	v_fmac_f32_e32 v178, v179, v178
	v_div_scale_f32 v179, vcc, 1.0, v175, 1.0
	v_mul_f32_e32 v180, v179, v178
	v_fma_f32 v181, -v177, v180, v179
	v_fmac_f32_e32 v180, v181, v178
	v_fma_f32 v177, -v177, v180, v179
	v_div_fmas_f32 v177, v177, v178, v180
	v_div_fixup_f32 v175, v177, v175, 1.0
	v_mul_f32_e32 v174, v175, v174
	v_mul_f32_e32 v174, v174, v176
	v_bfe_u32 v176, v174, 16, 1
	v_add3_u32 v174, v174, v176, s5
	v_perm_b32 v230, v224, v216, v242
	v_mul_f32_e32 v231, 0xbfb8aa3b, v230
	v_exp_f32_e32 v231, v231
	v_mul_f32_e32 v233, v42, v232
	v_mul_f32_e32 v233, v187, v233
	v_add_f32_e32 v231, 1.0, v231
	v_div_scale_f32 v234, s[0:1], v231, v231, 1.0
	v_rcp_f32_e32 v235, v234
	s_nop 0
	v_fma_f32 v236, -v234, v235, 1.0
	v_fmac_f32_e32 v235, v236, v235
	v_div_scale_f32 v236, vcc, 1.0, v231, 1.0
	v_mul_f32_e32 v237, v236, v235
	v_fma_f32 v109, -v234, v237, v236
	v_fmac_f32_e32 v237, v109, v235
	v_fma_f32 v234, -v234, v237, v236
	v_div_fmas_f32 v234, v234, v235, v237
	v_div_fixup_f32 v231, v234, v231, 1.0
	v_mul_f32_e32 v230, v231, v230
	v_mul_f32_e32 v230, v230, v233
	v_bfe_u32 v233, v230, 16, 1
	v_add3_u32 v230, v230, v233, s5
	v_bfi_b32 v246, v240, v174, v230
	v_bfi_b32 v248, v240, v230, v174
	s_nop 0
	v_mov_b32_dpp v247, v246 quad_perm:[1,0,3,2] row_mask:0xf bank_mask:0xf
	s_nop 0
	v_perm_b32 v248, v247, v248, v243
	global_store_dword v[120:121], v248, off offset:128
	v_perm_b32 v174, v225, v217, v241
	v_mul_f32_e32 v175, 0xbfb8aa3b, v174
	v_exp_f32_e32 v175, v175
	v_mul_f32_e32 v176, v38, v232
	v_mul_f32_e32 v176, v188, v176
	v_add_f32_e32 v175, 1.0, v175
	v_div_scale_f32 v177, s[0:1], v175, v175, 1.0
	v_rcp_f32_e32 v178, v177
	s_nop 0
	v_fma_f32 v179, -v177, v178, 1.0
	v_fmac_f32_e32 v178, v179, v178
	v_div_scale_f32 v179, vcc, 1.0, v175, 1.0
	v_mul_f32_e32 v180, v179, v178
	v_fma_f32 v181, -v177, v180, v179
	v_fmac_f32_e32 v180, v181, v178
	v_fma_f32 v177, -v177, v180, v179
	v_div_fmas_f32 v177, v177, v178, v180
	v_div_fixup_f32 v175, v177, v175, 1.0
	v_mul_f32_e32 v174, v175, v174
	v_mul_f32_e32 v174, v174, v176
	v_bfe_u32 v176, v174, 16, 1
	v_add3_u32 v174, v174, v176, s5
	v_perm_b32 v230, v225, v217, v242
	v_mul_f32_e32 v231, 0xbfb8aa3b, v230
	v_exp_f32_e32 v231, v231
	v_mul_f32_e32 v233, v34, v232
	v_mul_f32_e32 v233, v189, v233
	v_add_f32_e32 v231, 1.0, v231
	v_div_scale_f32 v234, s[0:1], v231, v231, 1.0
	v_rcp_f32_e32 v235, v234
	s_nop 0
	v_fma_f32 v236, -v234, v235, 1.0
	v_fmac_f32_e32 v235, v236, v235
	v_div_scale_f32 v236, vcc, 1.0, v231, 1.0
	v_mul_f32_e32 v237, v236, v235
	v_fma_f32 v109, -v234, v237, v236
	v_fmac_f32_e32 v237, v109, v235
	v_fma_f32 v234, -v234, v237, v236
	v_div_fmas_f32 v234, v234, v235, v237
	v_div_fixup_f32 v231, v234, v231, 1.0
	v_mul_f32_e32 v230, v231, v230
	v_mul_f32_e32 v230, v230, v233
	v_bfe_u32 v233, v230, 16, 1
	v_add3_u32 v230, v230, v233, s5
	v_bfi_b32 v246, v240, v174, v230
	v_bfi_b32 v248, v240, v230, v174
	s_nop 0
	v_mov_b32_dpp v247, v246 quad_perm:[1,0,3,2] row_mask:0xf bank_mask:0xf
	s_nop 0
	v_perm_b32 v248, v247, v248, v243
	global_store_dword v[120:121], v248, off offset:192
	v_perm_b32 v174, v226, v218, v241
	v_mul_f32_e32 v175, 0xbfb8aa3b, v174
	v_exp_f32_e32 v175, v175
	v_mul_f32_e32 v176, v30, v232
	v_mul_f32_e32 v176, v190, v176
	v_add_f32_e32 v175, 1.0, v175
	v_div_scale_f32 v177, s[0:1], v175, v175, 1.0
	v_rcp_f32_e32 v178, v177
	s_nop 0
	v_fma_f32 v179, -v177, v178, 1.0
	v_fmac_f32_e32 v178, v179, v178
	v_div_scale_f32 v179, vcc, 1.0, v175, 1.0
	v_mul_f32_e32 v180, v179, v178
	v_fma_f32 v181, -v177, v180, v179
	v_fmac_f32_e32 v180, v181, v178
	v_fma_f32 v177, -v177, v180, v179
	v_div_fmas_f32 v177, v177, v178, v180
	v_div_fixup_f32 v175, v177, v175, 1.0
	v_mul_f32_e32 v174, v175, v174
	v_mul_f32_e32 v174, v174, v176
	v_bfe_u32 v176, v174, 16, 1
	v_add3_u32 v174, v174, v176, s5
	v_perm_b32 v230, v226, v218, v242
	v_mul_f32_e32 v231, 0xbfb8aa3b, v230
	v_exp_f32_e32 v231, v231
	v_mul_f32_e32 v233, v26, v232
	v_mul_f32_e32 v233, v191, v233
	v_add_f32_e32 v231, 1.0, v231
	v_div_scale_f32 v234, s[0:1], v231, v231, 1.0
	v_rcp_f32_e32 v235, v234
	s_nop 0
	v_fma_f32 v236, -v234, v235, 1.0
	v_fmac_f32_e32 v235, v236, v235
	v_div_scale_f32 v236, vcc, 1.0, v231, 1.0
	v_mul_f32_e32 v237, v236, v235
	v_fma_f32 v109, -v234, v237, v236
	v_fmac_f32_e32 v237, v109, v235
	v_fma_f32 v234, -v234, v237, v236
	v_div_fmas_f32 v234, v234, v235, v237
	v_div_fixup_f32 v231, v234, v231, 1.0
	v_mul_f32_e32 v230, v231, v230
	v_mul_f32_e32 v230, v230, v233
	v_bfe_u32 v233, v230, 16, 1
	v_add3_u32 v230, v230, v233, s5
	v_bfi_b32 v246, v240, v174, v230
	v_bfi_b32 v248, v240, v230, v174
	s_nop 0
	v_mov_b32_dpp v247, v246 quad_perm:[1,0,3,2] row_mask:0xf bank_mask:0xf
	s_nop 0
	v_perm_b32 v248, v247, v248, v243
	global_store_dword v[120:121], v248, off offset:256
	v_perm_b32 v174, v227, v219, v241
	v_mul_f32_e32 v175, 0xbfb8aa3b, v174
	v_exp_f32_e32 v175, v175
	v_mul_f32_e32 v176, v22, v232
	v_mul_f32_e32 v176, v192, v176
	v_add_f32_e32 v175, 1.0, v175
	v_div_scale_f32 v177, s[0:1], v175, v175, 1.0
	v_rcp_f32_e32 v178, v177
	s_nop 0
	v_fma_f32 v179, -v177, v178, 1.0
	v_fmac_f32_e32 v178, v179, v178
	v_div_scale_f32 v179, vcc, 1.0, v175, 1.0
	v_mul_f32_e32 v180, v179, v178
	v_fma_f32 v181, -v177, v180, v179
	v_fmac_f32_e32 v180, v181, v178
	v_fma_f32 v177, -v177, v180, v179
	v_div_fmas_f32 v177, v177, v178, v180
	v_div_fixup_f32 v175, v177, v175, 1.0
	v_mul_f32_e32 v174, v175, v174
	v_mul_f32_e32 v174, v174, v176
	v_bfe_u32 v176, v174, 16, 1
	v_add3_u32 v174, v174, v176, s5
	v_perm_b32 v230, v227, v219, v242
	v_mul_f32_e32 v231, 0xbfb8aa3b, v230
	v_exp_f32_e32 v231, v231
	v_mul_f32_e32 v233, v18, v232
	v_mul_f32_e32 v233, v193, v233
	v_add_f32_e32 v231, 1.0, v231
	v_div_scale_f32 v234, s[0:1], v231, v231, 1.0
	v_rcp_f32_e32 v235, v234
	s_nop 0
	v_fma_f32 v236, -v234, v235, 1.0
	v_fmac_f32_e32 v235, v236, v235
	v_div_scale_f32 v236, vcc, 1.0, v231, 1.0
	v_mul_f32_e32 v237, v236, v235
	v_fma_f32 v109, -v234, v237, v236
	v_fmac_f32_e32 v237, v109, v235
	v_fma_f32 v234, -v234, v237, v236
	v_div_fmas_f32 v234, v234, v235, v237
	v_div_fixup_f32 v231, v234, v231, 1.0
	v_mul_f32_e32 v230, v231, v230
	v_mul_f32_e32 v230, v230, v233
	v_bfe_u32 v233, v230, 16, 1
	v_add3_u32 v230, v230, v233, s5
	v_bfi_b32 v246, v240, v174, v230
	v_bfi_b32 v248, v240, v230, v174
	s_nop 0
	v_mov_b32_dpp v247, v246 quad_perm:[1,0,3,2] row_mask:0xf bank_mask:0xf
	s_nop 0
	v_perm_b32 v248, v247, v248, v243
	global_store_dword v[120:121], v248, off offset:320
	v_perm_b32 v174, v228, v220, v241
	v_mul_f32_e32 v175, 0xbfb8aa3b, v174
	v_exp_f32_e32 v175, v175
	v_mul_f32_e32 v176, v14, v232
	v_mul_f32_e32 v176, v194, v176
	v_add_f32_e32 v175, 1.0, v175
	v_div_scale_f32 v177, s[0:1], v175, v175, 1.0
	v_rcp_f32_e32 v178, v177
	s_nop 0
	v_fma_f32 v179, -v177, v178, 1.0
	v_fmac_f32_e32 v178, v179, v178
	v_div_scale_f32 v179, vcc, 1.0, v175, 1.0
	v_mul_f32_e32 v180, v179, v178
	v_fma_f32 v181, -v177, v180, v179
	v_fmac_f32_e32 v180, v181, v178
	v_fma_f32 v177, -v177, v180, v179
	v_div_fmas_f32 v177, v177, v178, v180
	v_div_fixup_f32 v175, v177, v175, 1.0
	v_mul_f32_e32 v174, v175, v174
	v_mul_f32_e32 v174, v174, v176
	v_bfe_u32 v176, v174, 16, 1
	v_add3_u32 v174, v174, v176, s5
	v_perm_b32 v230, v228, v220, v242
	v_mul_f32_e32 v231, 0xbfb8aa3b, v230
	v_exp_f32_e32 v231, v231
	v_mul_f32_e32 v233, v10, v232
	v_mul_f32_e32 v233, v195, v233
	v_add_f32_e32 v231, 1.0, v231
	v_div_scale_f32 v234, s[0:1], v231, v231, 1.0
	v_rcp_f32_e32 v235, v234
	s_nop 0
	v_fma_f32 v236, -v234, v235, 1.0
	v_fmac_f32_e32 v235, v236, v235
	v_div_scale_f32 v236, vcc, 1.0, v231, 1.0
	v_mul_f32_e32 v237, v236, v235
	v_fma_f32 v109, -v234, v237, v236
	v_fmac_f32_e32 v237, v109, v235
	v_fma_f32 v234, -v234, v237, v236
	v_div_fmas_f32 v234, v234, v235, v237
	v_div_fixup_f32 v231, v234, v231, 1.0
	v_mul_f32_e32 v230, v231, v230
	v_mul_f32_e32 v230, v230, v233
	v_bfe_u32 v233, v230, 16, 1
	v_add3_u32 v230, v230, v233, s5
	v_bfi_b32 v246, v240, v174, v230
	v_bfi_b32 v248, v240, v230, v174
	s_nop 0
	v_mov_b32_dpp v247, v246 quad_perm:[1,0,3,2] row_mask:0xf bank_mask:0xf
	s_nop 0
	v_perm_b32 v248, v247, v248, v243
	global_store_dword v[120:121], v248, off offset:384
	v_perm_b32 v174, v229, v221, v241
	v_mul_f32_e32 v175, 0xbfb8aa3b, v174
	v_exp_f32_e32 v175, v175
	v_mul_f32_e32 v176, v6, v232
	v_mul_f32_e32 v176, v196, v176
	v_add_f32_e32 v175, 1.0, v175
	v_div_scale_f32 v177, s[0:1], v175, v175, 1.0
	v_rcp_f32_e32 v178, v177
	s_nop 0
	v_fma_f32 v179, -v177, v178, 1.0
	v_fmac_f32_e32 v178, v179, v178
	v_div_scale_f32 v179, vcc, 1.0, v175, 1.0
	v_mul_f32_e32 v180, v179, v178
	v_fma_f32 v181, -v177, v180, v179
	v_fmac_f32_e32 v180, v181, v178
	v_fma_f32 v177, -v177, v180, v179
	v_div_fmas_f32 v177, v177, v178, v180
	v_div_fixup_f32 v175, v177, v175, 1.0
	v_mul_f32_e32 v174, v175, v174
	v_mul_f32_e32 v174, v174, v176
	v_bfe_u32 v176, v174, 16, 1
	v_add3_u32 v174, v174, v176, s5
	v_perm_b32 v230, v229, v221, v242
	v_mul_f32_e32 v231, 0xbfb8aa3b, v230
	v_exp_f32_e32 v231, v231
	v_mul_f32_e32 v233, v2, v232
	v_mul_f32_e32 v233, v197, v233
	v_add_f32_e32 v231, 1.0, v231
	v_div_scale_f32 v234, s[0:1], v231, v231, 1.0
	v_rcp_f32_e32 v235, v234
	s_nop 0
	v_fma_f32 v236, -v234, v235, 1.0
	v_fmac_f32_e32 v235, v236, v235
	v_div_scale_f32 v236, vcc, 1.0, v231, 1.0
	v_mul_f32_e32 v237, v236, v235
	v_fma_f32 v109, -v234, v237, v236
	v_fmac_f32_e32 v237, v109, v235
	v_fma_f32 v234, -v234, v237, v236
	v_div_fmas_f32 v234, v234, v235, v237
	v_div_fixup_f32 v231, v234, v231, 1.0
	v_mul_f32_e32 v230, v231, v230
	v_mul_f32_e32 v230, v230, v233
	v_bfe_u32 v233, v230, 16, 1
	v_add3_u32 v230, v230, v233, s5
	v_bfi_b32 v246, v240, v174, v230
	v_bfi_b32 v248, v240, v230, v174
	s_nop 0
	v_mov_b32_dpp v247, v246 quad_perm:[1,0,3,2] row_mask:0xf bank_mask:0xf
	s_nop 0
	v_perm_b32 v248, v247, v248, v243
	global_store_dword v[120:121], v248, off offset:448
	global_load_dword v214, v[118:119], off offset:0
	global_load_dword v215, v[118:119], off offset:64
	global_load_dword v216, v[118:119], off offset:128
	global_load_dword v217, v[118:119], off offset:192
	global_load_dword v218, v[118:119], off offset:256
	global_load_dword v219, v[118:119], off offset:320
	global_load_dword v220, v[118:119], off offset:384
	global_load_dword v221, v[118:119], off offset:448
	v_mov_b32_e32 v120, v114
	v_mov_b32_e32 v121, v115
	s_waitcnt vmcnt(16)
	v_mov_b32_dpp v206, v198 quad_perm:[1,0,3,2] row_mask:0xf bank_mask:0xf
	v_mov_b32_dpp v207, v199 quad_perm:[1,0,3,2] row_mask:0xf bank_mask:0xf
	v_mov_b32_dpp v208, v200 quad_perm:[1,0,3,2] row_mask:0xf bank_mask:0xf
	v_mov_b32_dpp v209, v201 quad_perm:[1,0,3,2] row_mask:0xf bank_mask:0xf
	v_mov_b32_dpp v210, v202 quad_perm:[1,0,3,2] row_mask:0xf bank_mask:0xf
	v_mov_b32_dpp v211, v203 quad_perm:[1,0,3,2] row_mask:0xf bank_mask:0xf
	v_mov_b32_dpp v212, v204 quad_perm:[1,0,3,2] row_mask:0xf bank_mask:0xf
	v_mov_b32_dpp v213, v205 quad_perm:[1,0,3,2] row_mask:0xf bank_mask:0xf
	v_perm_b32 v231, v206, v198, v241
	v_add_f32_e32 v63, v63, v231
	v_add_f32_e32 v230, 0, v63
	v_perm_b32 v233, v206, v198, v242
	v_add_f32_e32 v59, v59, v233
	v_add_f32_e32 v230, v230, v59
	v_perm_b32 v231, v207, v199, v241
	v_add_f32_e32 v55, v55, v231
	v_add_f32_e32 v230, v230, v55
	v_perm_b32 v233, v207, v199, v242
	v_add_f32_e32 v51, v51, v233
	v_add_f32_e32 v230, v230, v51
	v_perm_b32 v231, v208, v200, v241
	v_add_f32_e32 v47, v47, v231
	v_add_f32_e32 v230, v230, v47
	v_perm_b32 v233, v208, v200, v242
	v_add_f32_e32 v43, v43, v233
	v_add_f32_e32 v230, v230, v43
	v_perm_b32 v231, v209, v201, v241
	v_add_f32_e32 v39, v39, v231
	v_add_f32_e32 v230, v230, v39
	v_perm_b32 v233, v209, v201, v242
	v_add_f32_e32 v35, v35, v233
	v_add_f32_e32 v230, v230, v35
	v_perm_b32 v231, v210, v202, v241
	v_add_f32_e32 v31, v31, v231
	v_add_f32_e32 v230, v230, v31
	v_perm_b32 v233, v210, v202, v242
	v_add_f32_e32 v27, v27, v233
	v_add_f32_e32 v230, v230, v27
	v_perm_b32 v231, v211, v203, v241
	v_add_f32_e32 v23, v23, v231
	v_add_f32_e32 v230, v230, v23
	v_perm_b32 v233, v211, v203, v242
	v_add_f32_e32 v19, v19, v233
	v_add_f32_e32 v230, v230, v19
	v_perm_b32 v231, v212, v204, v241
	v_add_f32_e32 v15, v15, v231
	v_add_f32_e32 v230, v230, v15
	v_perm_b32 v233, v212, v204, v242
	v_add_f32_e32 v11, v11, v233
	v_add_f32_e32 v230, v230, v11
	v_perm_b32 v231, v213, v205, v241
	v_add_f32_e32 v7, v7, v231
	v_add_f32_e32 v230, v230, v7
	v_perm_b32 v233, v213, v205, v242
	v_add_f32_e32 v3, v3, v233
	v_add_f32_e32 v230, v230, v3
	v_or_b32_e32 v116, 2, v112
	v_mov_b32_e32 v117, s11
	v_lshlrev_b64 v[114:115], 12, v[116:117]
	v_lshl_add_u64 v[114:115], s[78:79], 0, v[114:115]
	v_lshl_add_u64 v[114:115], v[114:115], 0, s[96:97]
	v_lshl_add_u64 v[114:115], v[114:115], 0, v[110:111]
	v_lshl_add_u64 v[114:115], v[114:115], 0, s[80:81]
	v_lshlrev_b64 v[118:119], 13, v[116:117]
	v_lshl_add_u64 v[118:119], s[92:93], 0, v[118:119]
	v_lshl_add_u64 v[118:119], v[118:119], 0, s[96:97]
	v_lshl_add_u64 v[118:119], v[118:119], 0, v[110:111]
	v_lshl_add_u64 v[118:119], v[118:119], 0, s[90:91]
	v_lshl_add_u64 v[114:115], v[114:115], 0, v[244:245]
	v_lshl_add_u64 v[118:119], v[118:119], 0, v[244:245]
	global_load_dword v198, v[114:115], off offset:0
	global_load_dword v199, v[114:115], off offset:64
	global_load_dword v200, v[114:115], off offset:128
	global_load_dword v201, v[114:115], off offset:192
	global_load_dword v202, v[114:115], off offset:256
	global_load_dword v203, v[114:115], off offset:320
	global_load_dword v204, v[114:115], off offset:384
	global_load_dword v205, v[114:115], off offset:448
	s_nop 1
	v_add_f32_dpp v230, v230, v230 row_ror:8 row_mask:0xf bank_mask:0xf bound_ctrl:1
	s_nop 1
	v_add_f32_dpp v230, v230, v230 row_ror:4 row_mask:0xf bank_mask:0xf bound_ctrl:1
	s_nop 1
	v_add_f32_dpp v230, v230, v230 row_ror:2 row_mask:0xf bank_mask:0xf bound_ctrl:1
	s_nop 1
	v_add_f32_dpp v230, v230, v230 row_ror:1 row_mask:0xf bank_mask:0xf bound_ctrl:1
	v_fmac_f32_e32 v59, 0xbb800000, v230
	v_mul_f32_e32 v231, v59, v59
	v_fmac_f32_e32 v63, 0xbb800000, v230
	v_fmac_f32_e32 v231, v63, v63
	v_fmac_f32_e32 v55, 0xbb800000, v230
	v_fmac_f32_e32 v231, v55, v55
	v_fmac_f32_e32 v51, 0xbb800000, v230
	v_fmac_f32_e32 v231, v51, v51
	v_fmac_f32_e32 v47, 0xbb800000, v230
	v_fmac_f32_e32 v231, v47, v47
	v_fmac_f32_e32 v43, 0xbb800000, v230
	v_fmac_f32_e32 v231, v43, v43
	v_fmac_f32_e32 v39, 0xbb800000, v230
	v_fmac_f32_e32 v231, v39, v39
	v_fmac_f32_e32 v35, 0xbb800000, v230
	v_fmac_f32_e32 v231, v35, v35
	v_fmac_f32_e32 v31, 0xbb800000, v230
	v_fmac_f32_e32 v231, v31, v31
	v_fmac_f32_e32 v27, 0xbb800000, v230
	v_fmac_f32_e32 v231, v27, v27
	v_fmac_f32_e32 v23, 0xbb800000, v230
	v_fmac_f32_e32 v231, v23, v23
	v_fmac_f32_e32 v19, 0xbb800000, v230
	v_fmac_f32_e32 v231, v19, v19
	v_fmac_f32_e32 v15, 0xbb800000, v230
	v_fmac_f32_e32 v231, v15, v15
	v_fmac_f32_e32 v11, 0xbb800000, v230
	v_fmac_f32_e32 v231, v11, v11
	v_fmac_f32_e32 v7, 0xbb800000, v230
	v_fmac_f32_e32 v231, v7, v7
	v_fmac_f32_e32 v3, 0xbb800000, v230
	v_fmac_f32_e32 v231, v3, v3
	s_nop 1
	v_add_f32_dpp v232, v231, v231 row_ror:8 row_mask:0xf bank_mask:0xf bound_ctrl:1
	s_nop 1
	v_add_f32_dpp v232, v232, v232 row_ror:4 row_mask:0xf bank_mask:0xf bound_ctrl:1
	s_nop 1
	v_add_f32_dpp v232, v232, v232 row_ror:2 row_mask:0xf bank_mask:0xf bound_ctrl:1
	s_nop 1
	v_add_f32_dpp v232, v232, v232 row_ror:1 row_mask:0xf bank_mask:0xf bound_ctrl:1
	v_fmamk_f32 v232, v232, 0x3b800000, v169
	v_cmp_gt_f32_e32 vcc, s7, v232
	v_mul_f32_e32 v233, 0x4f800000, v232
	s_nop 0
	v_cndmask_b32_e32 v232, v232, v233, vcc
	v_sqrt_f32_e32 v233, v232
	s_nop 0
	v_add_u32_e32 v234, -1, v233
	v_fma_f32 v235, -v234, v233, v232
	v_cmp_ge_f32_e64 s[0:1], 0, v235
	v_add_u32_e32 v235, 1, v233
	s_nop 0
	v_cndmask_b32_e64 v234, v233, v234, s[0:1]
	v_fma_f32 v233, -v235, v233, v232
	v_cmp_lt_f32_e64 s[0:1], 0, v233
	s_nop 1
	v_cndmask_b32_e64 v233, v234, v235, s[0:1]
	v_mul_f32_e32 v234, 0x37800000, v233
	s_nop 0
	v_cndmask_b32_e32 v233, v233, v234, vcc
	v_cmp_class_f32_e32 vcc, v232, v170
	s_nop 1
	v_cndmask_b32_e32 v232, v233, v232, vcc
	v_div_scale_f32 v233, s[0:1], v232, v232, 1.0
	v_rcp_f32_e32 v234, v233
	s_nop 0
	v_fma_f32 v235, -v233, v234, 1.0
	v_fmac_f32_e32 v234, v235, v234
	v_div_scale_f32 v235, vcc, 1.0, v232, 1.0
	v_mul_f32_e32 v236, v235, v234
	v_fma_f32 v237, -v233, v236, v235
	v_fmac_f32_e32 v236, v237, v234
	v_fma_f32 v233, -v233, v236, v235
	v_div_fmas_f32 v233, v233, v234, v236
	v_div_fixup_f32 v232, v233, v232, 1.0
	s_waitcnt vmcnt(8)
	v_mov_b32_dpp v222, v214 quad_perm:[1,0,3,2] row_mask:0xf bank_mask:0xf
	v_mov_b32_dpp v223, v215 quad_perm:[1,0,3,2] row_mask:0xf bank_mask:0xf
	v_mov_b32_dpp v224, v216 quad_perm:[1,0,3,2] row_mask:0xf bank_mask:0xf
	v_mov_b32_dpp v225, v217 quad_perm:[1,0,3,2] row_mask:0xf bank_mask:0xf
	v_mov_b32_dpp v226, v218 quad_perm:[1,0,3,2] row_mask:0xf bank_mask:0xf
	v_mov_b32_dpp v227, v219 quad_perm:[1,0,3,2] row_mask:0xf bank_mask:0xf
	v_mov_b32_dpp v228, v220 quad_perm:[1,0,3,2] row_mask:0xf bank_mask:0xf
	v_mov_b32_dpp v229, v221 quad_perm:[1,0,3,2] row_mask:0xf bank_mask:0xf
	v_perm_b32 v174, v222, v214, v241
	v_mul_f32_e32 v175, 0xbfb8aa3b, v174
	v_exp_f32_e32 v175, v175
	v_mul_f32_e32 v176, v63, v232
	v_mul_f32_e32 v176, v182, v176
	v_add_f32_e32 v175, 1.0, v175
	v_div_scale_f32 v177, s[0:1], v175, v175, 1.0
	v_rcp_f32_e32 v178, v177
	s_nop 0
	v_fma_f32 v179, -v177, v178, 1.0
	v_fmac_f32_e32 v178, v179, v178
	v_div_scale_f32 v179, vcc, 1.0, v175, 1.0
	v_mul_f32_e32 v180, v179, v178
	v_fma_f32 v181, -v177, v180, v179
	v_fmac_f32_e32 v180, v181, v178
	v_fma_f32 v177, -v177, v180, v179
	v_div_fmas_f32 v177, v177, v178, v180
	v_div_fixup_f32 v175, v177, v175, 1.0
	v_mul_f32_e32 v174, v175, v174
	v_mul_f32_e32 v174, v174, v176
	v_bfe_u32 v176, v174, 16, 1
	v_add3_u32 v174, v174, v176, s5
	v_perm_b32 v230, v222, v214, v242
	v_mul_f32_e32 v231, 0xbfb8aa3b, v230
	v_exp_f32_e32 v231, v231
	v_mul_f32_e32 v233, v59, v232
	v_mul_f32_e32 v233, v183, v233
	v_add_f32_e32 v231, 1.0, v231
	v_div_scale_f32 v234, s[0:1], v231, v231, 1.0
	v_rcp_f32_e32 v235, v234
	s_nop 0
	v_fma_f32 v236, -v234, v235, 1.0
	v_fmac_f32_e32 v235, v236, v235
	v_div_scale_f32 v236, vcc, 1.0, v231, 1.0
	v_mul_f32_e32 v237, v236, v235
	v_fma_f32 v109, -v234, v237, v236
	v_fmac_f32_e32 v237, v109, v235
	v_fma_f32 v234, -v234, v237, v236
	v_div_fmas_f32 v234, v234, v235, v237
	v_div_fixup_f32 v231, v234, v231, 1.0
	v_mul_f32_e32 v230, v231, v230
	v_mul_f32_e32 v230, v230, v233
	v_bfe_u32 v233, v230, 16, 1
	v_add3_u32 v230, v230, v233, s5
	v_bfi_b32 v246, v240, v174, v230
	v_bfi_b32 v248, v240, v230, v174
	s_nop 0
	v_mov_b32_dpp v247, v246 quad_perm:[1,0,3,2] row_mask:0xf bank_mask:0xf
	s_nop 0
	v_perm_b32 v248, v247, v248, v243
	global_store_dword v[120:121], v248, off offset:0
	v_perm_b32 v174, v223, v215, v241
	v_mul_f32_e32 v175, 0xbfb8aa3b, v174
	v_exp_f32_e32 v175, v175
	v_mul_f32_e32 v176, v55, v232
	v_mul_f32_e32 v176, v184, v176
	v_add_f32_e32 v175, 1.0, v175
	v_div_scale_f32 v177, s[0:1], v175, v175, 1.0
	v_rcp_f32_e32 v178, v177
	s_nop 0
	v_fma_f32 v179, -v177, v178, 1.0
	v_fmac_f32_e32 v178, v179, v178
	v_div_scale_f32 v179, vcc, 1.0, v175, 1.0
	v_mul_f32_e32 v180, v179, v178
	v_fma_f32 v181, -v177, v180, v179
	v_fmac_f32_e32 v180, v181, v178
	v_fma_f32 v177, -v177, v180, v179
	v_div_fmas_f32 v177, v177, v178, v180
	v_div_fixup_f32 v175, v177, v175, 1.0
	v_mul_f32_e32 v174, v175, v174
	v_mul_f32_e32 v174, v174, v176
	v_bfe_u32 v176, v174, 16, 1
	v_add3_u32 v174, v174, v176, s5
	v_perm_b32 v230, v223, v215, v242
	v_mul_f32_e32 v231, 0xbfb8aa3b, v230
	v_exp_f32_e32 v231, v231
	v_mul_f32_e32 v233, v51, v232
	v_mul_f32_e32 v233, v185, v233
	v_add_f32_e32 v231, 1.0, v231
	v_div_scale_f32 v234, s[0:1], v231, v231, 1.0
	v_rcp_f32_e32 v235, v234
	s_nop 0
	v_fma_f32 v236, -v234, v235, 1.0
	v_fmac_f32_e32 v235, v236, v235
	v_div_scale_f32 v236, vcc, 1.0, v231, 1.0
	v_mul_f32_e32 v237, v236, v235
	v_fma_f32 v109, -v234, v237, v236
	v_fmac_f32_e32 v237, v109, v235
	v_fma_f32 v234, -v234, v237, v236
	v_div_fmas_f32 v234, v234, v235, v237
	v_div_fixup_f32 v231, v234, v231, 1.0
	v_mul_f32_e32 v230, v231, v230
	v_mul_f32_e32 v230, v230, v233
	v_bfe_u32 v233, v230, 16, 1
	v_add3_u32 v230, v230, v233, s5
	v_bfi_b32 v246, v240, v174, v230
	v_bfi_b32 v248, v240, v230, v174
	s_nop 0
	v_mov_b32_dpp v247, v246 quad_perm:[1,0,3,2] row_mask:0xf bank_mask:0xf
	s_nop 0
	v_perm_b32 v248, v247, v248, v243
	global_store_dword v[120:121], v248, off offset:64
	v_perm_b32 v174, v224, v216, v241
	v_mul_f32_e32 v175, 0xbfb8aa3b, v174
	v_exp_f32_e32 v175, v175
	v_mul_f32_e32 v176, v47, v232
	v_mul_f32_e32 v176, v186, v176
	v_add_f32_e32 v175, 1.0, v175
	v_div_scale_f32 v177, s[0:1], v175, v175, 1.0
	v_rcp_f32_e32 v178, v177
	s_nop 0
	v_fma_f32 v179, -v177, v178, 1.0
	v_fmac_f32_e32 v178, v179, v178
	v_div_scale_f32 v179, vcc, 1.0, v175, 1.0
	v_mul_f32_e32 v180, v179, v178
	v_fma_f32 v181, -v177, v180, v179
	v_fmac_f32_e32 v180, v181, v178
	v_fma_f32 v177, -v177, v180, v179
	v_div_fmas_f32 v177, v177, v178, v180
	v_div_fixup_f32 v175, v177, v175, 1.0
	v_mul_f32_e32 v174, v175, v174
	v_mul_f32_e32 v174, v174, v176
	v_bfe_u32 v176, v174, 16, 1
	v_add3_u32 v174, v174, v176, s5
	v_perm_b32 v230, v224, v216, v242
	v_mul_f32_e32 v231, 0xbfb8aa3b, v230
	v_exp_f32_e32 v231, v231
	v_mul_f32_e32 v233, v43, v232
	v_mul_f32_e32 v233, v187, v233
	v_add_f32_e32 v231, 1.0, v231
	v_div_scale_f32 v234, s[0:1], v231, v231, 1.0
	v_rcp_f32_e32 v235, v234
	s_nop 0
	v_fma_f32 v236, -v234, v235, 1.0
	v_fmac_f32_e32 v235, v236, v235
	v_div_scale_f32 v236, vcc, 1.0, v231, 1.0
	v_mul_f32_e32 v237, v236, v235
	v_fma_f32 v109, -v234, v237, v236
	v_fmac_f32_e32 v237, v109, v235
	v_fma_f32 v234, -v234, v237, v236
	v_div_fmas_f32 v234, v234, v235, v237
	v_div_fixup_f32 v231, v234, v231, 1.0
	v_mul_f32_e32 v230, v231, v230
	v_mul_f32_e32 v230, v230, v233
	v_bfe_u32 v233, v230, 16, 1
	v_add3_u32 v230, v230, v233, s5
	v_bfi_b32 v246, v240, v174, v230
	v_bfi_b32 v248, v240, v230, v174
	s_nop 0
	v_mov_b32_dpp v247, v246 quad_perm:[1,0,3,2] row_mask:0xf bank_mask:0xf
	s_nop 0
	v_perm_b32 v248, v247, v248, v243
	global_store_dword v[120:121], v248, off offset:128
	v_perm_b32 v174, v225, v217, v241
	v_mul_f32_e32 v175, 0xbfb8aa3b, v174
	v_exp_f32_e32 v175, v175
	v_mul_f32_e32 v176, v39, v232
	v_mul_f32_e32 v176, v188, v176
	v_add_f32_e32 v175, 1.0, v175
	v_div_scale_f32 v177, s[0:1], v175, v175, 1.0
	v_rcp_f32_e32 v178, v177
	s_nop 0
	v_fma_f32 v179, -v177, v178, 1.0
	v_fmac_f32_e32 v178, v179, v178
	v_div_scale_f32 v179, vcc, 1.0, v175, 1.0
	v_mul_f32_e32 v180, v179, v178
	v_fma_f32 v181, -v177, v180, v179
	v_fmac_f32_e32 v180, v181, v178
	v_fma_f32 v177, -v177, v180, v179
	v_div_fmas_f32 v177, v177, v178, v180
	v_div_fixup_f32 v175, v177, v175, 1.0
	v_mul_f32_e32 v174, v175, v174
	v_mul_f32_e32 v174, v174, v176
	v_bfe_u32 v176, v174, 16, 1
	v_add3_u32 v174, v174, v176, s5
	v_perm_b32 v230, v225, v217, v242
	v_mul_f32_e32 v231, 0xbfb8aa3b, v230
	v_exp_f32_e32 v231, v231
	v_mul_f32_e32 v233, v35, v232
	v_mul_f32_e32 v233, v189, v233
	v_add_f32_e32 v231, 1.0, v231
	v_div_scale_f32 v234, s[0:1], v231, v231, 1.0
	v_rcp_f32_e32 v235, v234
	s_nop 0
	v_fma_f32 v236, -v234, v235, 1.0
	v_fmac_f32_e32 v235, v236, v235
	v_div_scale_f32 v236, vcc, 1.0, v231, 1.0
	v_mul_f32_e32 v237, v236, v235
	v_fma_f32 v109, -v234, v237, v236
	v_fmac_f32_e32 v237, v109, v235
	v_fma_f32 v234, -v234, v237, v236
	v_div_fmas_f32 v234, v234, v235, v237
	v_div_fixup_f32 v231, v234, v231, 1.0
	v_mul_f32_e32 v230, v231, v230
	v_mul_f32_e32 v230, v230, v233
	v_bfe_u32 v233, v230, 16, 1
	v_add3_u32 v230, v230, v233, s5
	v_bfi_b32 v246, v240, v174, v230
	v_bfi_b32 v248, v240, v230, v174
	s_nop 0
	v_mov_b32_dpp v247, v246 quad_perm:[1,0,3,2] row_mask:0xf bank_mask:0xf
	s_nop 0
	v_perm_b32 v248, v247, v248, v243
	global_store_dword v[120:121], v248, off offset:192
	v_perm_b32 v174, v226, v218, v241
	v_mul_f32_e32 v175, 0xbfb8aa3b, v174
	v_exp_f32_e32 v175, v175
	v_mul_f32_e32 v176, v31, v232
	v_mul_f32_e32 v176, v190, v176
	v_add_f32_e32 v175, 1.0, v175
	v_div_scale_f32 v177, s[0:1], v175, v175, 1.0
	v_rcp_f32_e32 v178, v177
	s_nop 0
	v_fma_f32 v179, -v177, v178, 1.0
	v_fmac_f32_e32 v178, v179, v178
	v_div_scale_f32 v179, vcc, 1.0, v175, 1.0
	v_mul_f32_e32 v180, v179, v178
	v_fma_f32 v181, -v177, v180, v179
	v_fmac_f32_e32 v180, v181, v178
	v_fma_f32 v177, -v177, v180, v179
	v_div_fmas_f32 v177, v177, v178, v180
	v_div_fixup_f32 v175, v177, v175, 1.0
	v_mul_f32_e32 v174, v175, v174
	v_mul_f32_e32 v174, v174, v176
	v_bfe_u32 v176, v174, 16, 1
	v_add3_u32 v174, v174, v176, s5
	v_perm_b32 v230, v226, v218, v242
	v_mul_f32_e32 v231, 0xbfb8aa3b, v230
	v_exp_f32_e32 v231, v231
	v_mul_f32_e32 v233, v27, v232
	v_mul_f32_e32 v233, v191, v233
	v_add_f32_e32 v231, 1.0, v231
	v_div_scale_f32 v234, s[0:1], v231, v231, 1.0
	v_rcp_f32_e32 v235, v234
	s_nop 0
	v_fma_f32 v236, -v234, v235, 1.0
	v_fmac_f32_e32 v235, v236, v235
	v_div_scale_f32 v236, vcc, 1.0, v231, 1.0
	v_mul_f32_e32 v237, v236, v235
	v_fma_f32 v109, -v234, v237, v236
	v_fmac_f32_e32 v237, v109, v235
	v_fma_f32 v234, -v234, v237, v236
	v_div_fmas_f32 v234, v234, v235, v237
	v_div_fixup_f32 v231, v234, v231, 1.0
	v_mul_f32_e32 v230, v231, v230
	v_mul_f32_e32 v230, v230, v233
	v_bfe_u32 v233, v230, 16, 1
	v_add3_u32 v230, v230, v233, s5
	v_bfi_b32 v246, v240, v174, v230
	v_bfi_b32 v248, v240, v230, v174
	s_nop 0
	v_mov_b32_dpp v247, v246 quad_perm:[1,0,3,2] row_mask:0xf bank_mask:0xf
	s_nop 0
	v_perm_b32 v248, v247, v248, v243
	global_store_dword v[120:121], v248, off offset:256
	v_perm_b32 v174, v227, v219, v241
	v_mul_f32_e32 v175, 0xbfb8aa3b, v174
	v_exp_f32_e32 v175, v175
	v_mul_f32_e32 v176, v23, v232
	v_mul_f32_e32 v176, v192, v176
	v_add_f32_e32 v175, 1.0, v175
	v_div_scale_f32 v177, s[0:1], v175, v175, 1.0
	v_rcp_f32_e32 v178, v177
	s_nop 0
	v_fma_f32 v179, -v177, v178, 1.0
	v_fmac_f32_e32 v178, v179, v178
	v_div_scale_f32 v179, vcc, 1.0, v175, 1.0
	v_mul_f32_e32 v180, v179, v178
	v_fma_f32 v181, -v177, v180, v179
	v_fmac_f32_e32 v180, v181, v178
	v_fma_f32 v177, -v177, v180, v179
	v_div_fmas_f32 v177, v177, v178, v180
	v_div_fixup_f32 v175, v177, v175, 1.0
	v_mul_f32_e32 v174, v175, v174
	v_mul_f32_e32 v174, v174, v176
	v_bfe_u32 v176, v174, 16, 1
	v_add3_u32 v174, v174, v176, s5
	v_perm_b32 v230, v227, v219, v242
	v_mul_f32_e32 v231, 0xbfb8aa3b, v230
	v_exp_f32_e32 v231, v231
	v_mul_f32_e32 v233, v19, v232
	v_mul_f32_e32 v233, v193, v233
	v_add_f32_e32 v231, 1.0, v231
	v_div_scale_f32 v234, s[0:1], v231, v231, 1.0
	v_rcp_f32_e32 v235, v234
	s_nop 0
	v_fma_f32 v236, -v234, v235, 1.0
	v_fmac_f32_e32 v235, v236, v235
	v_div_scale_f32 v236, vcc, 1.0, v231, 1.0
	v_mul_f32_e32 v237, v236, v235
	v_fma_f32 v109, -v234, v237, v236
	v_fmac_f32_e32 v237, v109, v235
	v_fma_f32 v234, -v234, v237, v236
	v_div_fmas_f32 v234, v234, v235, v237
	v_div_fixup_f32 v231, v234, v231, 1.0
	v_mul_f32_e32 v230, v231, v230
	v_mul_f32_e32 v230, v230, v233
	v_bfe_u32 v233, v230, 16, 1
	v_add3_u32 v230, v230, v233, s5
	v_bfi_b32 v246, v240, v174, v230
	v_bfi_b32 v248, v240, v230, v174
	s_nop 0
	v_mov_b32_dpp v247, v246 quad_perm:[1,0,3,2] row_mask:0xf bank_mask:0xf
	s_nop 0
	v_perm_b32 v248, v247, v248, v243
	global_store_dword v[120:121], v248, off offset:320
	v_perm_b32 v174, v228, v220, v241
	v_mul_f32_e32 v175, 0xbfb8aa3b, v174
	v_exp_f32_e32 v175, v175
	v_mul_f32_e32 v176, v15, v232
	v_mul_f32_e32 v176, v194, v176
	v_add_f32_e32 v175, 1.0, v175
	v_div_scale_f32 v177, s[0:1], v175, v175, 1.0
	v_rcp_f32_e32 v178, v177
	s_nop 0
	v_fma_f32 v179, -v177, v178, 1.0
	v_fmac_f32_e32 v178, v179, v178
	v_div_scale_f32 v179, vcc, 1.0, v175, 1.0
	v_mul_f32_e32 v180, v179, v178
	v_fma_f32 v181, -v177, v180, v179
	v_fmac_f32_e32 v180, v181, v178
	v_fma_f32 v177, -v177, v180, v179
	v_div_fmas_f32 v177, v177, v178, v180
	v_div_fixup_f32 v175, v177, v175, 1.0
	v_mul_f32_e32 v174, v175, v174
	v_mul_f32_e32 v174, v174, v176
	v_bfe_u32 v176, v174, 16, 1
	v_add3_u32 v174, v174, v176, s5
	v_perm_b32 v230, v228, v220, v242
	v_mul_f32_e32 v231, 0xbfb8aa3b, v230
	v_exp_f32_e32 v231, v231
	v_mul_f32_e32 v233, v11, v232
	v_mul_f32_e32 v233, v195, v233
	v_add_f32_e32 v231, 1.0, v231
	v_div_scale_f32 v234, s[0:1], v231, v231, 1.0
	v_rcp_f32_e32 v235, v234
	s_nop 0
	v_fma_f32 v236, -v234, v235, 1.0
	v_fmac_f32_e32 v235, v236, v235
	v_div_scale_f32 v236, vcc, 1.0, v231, 1.0
	v_mul_f32_e32 v237, v236, v235
	v_fma_f32 v109, -v234, v237, v236
	v_fmac_f32_e32 v237, v109, v235
	v_fma_f32 v234, -v234, v237, v236
	v_div_fmas_f32 v234, v234, v235, v237
	v_div_fixup_f32 v231, v234, v231, 1.0
	v_mul_f32_e32 v230, v231, v230
	v_mul_f32_e32 v230, v230, v233
	v_bfe_u32 v233, v230, 16, 1
	v_add3_u32 v230, v230, v233, s5
	v_bfi_b32 v246, v240, v174, v230
	v_bfi_b32 v248, v240, v230, v174
	s_nop 0
	v_mov_b32_dpp v247, v246 quad_perm:[1,0,3,2] row_mask:0xf bank_mask:0xf
	s_nop 0
	v_perm_b32 v248, v247, v248, v243
	global_store_dword v[120:121], v248, off offset:384
	v_perm_b32 v174, v229, v221, v241
	v_mul_f32_e32 v175, 0xbfb8aa3b, v174
	v_exp_f32_e32 v175, v175
	v_mul_f32_e32 v176, v7, v232
	v_mul_f32_e32 v176, v196, v176
	v_add_f32_e32 v175, 1.0, v175
	v_div_scale_f32 v177, s[0:1], v175, v175, 1.0
	v_rcp_f32_e32 v178, v177
	s_nop 0
	v_fma_f32 v179, -v177, v178, 1.0
	v_fmac_f32_e32 v178, v179, v178
	v_div_scale_f32 v179, vcc, 1.0, v175, 1.0
	v_mul_f32_e32 v180, v179, v178
	v_fma_f32 v181, -v177, v180, v179
	v_fmac_f32_e32 v180, v181, v178
	v_fma_f32 v177, -v177, v180, v179
	v_div_fmas_f32 v177, v177, v178, v180
	v_div_fixup_f32 v175, v177, v175, 1.0
	v_mul_f32_e32 v174, v175, v174
	v_mul_f32_e32 v174, v174, v176
	v_bfe_u32 v176, v174, 16, 1
	v_add3_u32 v174, v174, v176, s5
	v_perm_b32 v230, v229, v221, v242
	v_mul_f32_e32 v231, 0xbfb8aa3b, v230
	v_exp_f32_e32 v231, v231
	v_mul_f32_e32 v233, v3, v232
	v_mul_f32_e32 v233, v197, v233
	v_add_f32_e32 v231, 1.0, v231
	v_div_scale_f32 v234, s[0:1], v231, v231, 1.0
	v_rcp_f32_e32 v235, v234
	s_nop 0
	v_fma_f32 v236, -v234, v235, 1.0
	v_fmac_f32_e32 v235, v236, v235
	v_div_scale_f32 v236, vcc, 1.0, v231, 1.0
	v_mul_f32_e32 v237, v236, v235
	v_fma_f32 v109, -v234, v237, v236
	v_fmac_f32_e32 v237, v109, v235
	v_fma_f32 v234, -v234, v237, v236
	v_div_fmas_f32 v234, v234, v235, v237
	v_div_fixup_f32 v231, v234, v231, 1.0
	v_mul_f32_e32 v230, v231, v230
	v_mul_f32_e32 v230, v230, v233
	v_bfe_u32 v233, v230, 16, 1
	v_add3_u32 v230, v230, v233, s5
	v_bfi_b32 v246, v240, v174, v230
	v_bfi_b32 v248, v240, v230, v174
	s_nop 0
	v_mov_b32_dpp v247, v246 quad_perm:[1,0,3,2] row_mask:0xf bank_mask:0xf
	s_nop 0
	v_perm_b32 v248, v247, v248, v243
	global_store_dword v[120:121], v248, off offset:448
	global_load_dword v214, v[118:119], off offset:0
	global_load_dword v215, v[118:119], off offset:64
	global_load_dword v216, v[118:119], off offset:128
	global_load_dword v217, v[118:119], off offset:192
	global_load_dword v218, v[118:119], off offset:256
	global_load_dword v219, v[118:119], off offset:320
	global_load_dword v220, v[118:119], off offset:384
	global_load_dword v221, v[118:119], off offset:448
	v_mov_b32_e32 v120, v114
	v_mov_b32_e32 v121, v115
	s_waitcnt vmcnt(16)
	v_mov_b32_dpp v206, v198 quad_perm:[1,0,3,2] row_mask:0xf bank_mask:0xf
	v_mov_b32_dpp v207, v199 quad_perm:[1,0,3,2] row_mask:0xf bank_mask:0xf
	v_mov_b32_dpp v208, v200 quad_perm:[1,0,3,2] row_mask:0xf bank_mask:0xf
	v_mov_b32_dpp v209, v201 quad_perm:[1,0,3,2] row_mask:0xf bank_mask:0xf
	v_mov_b32_dpp v210, v202 quad_perm:[1,0,3,2] row_mask:0xf bank_mask:0xf
	v_mov_b32_dpp v211, v203 quad_perm:[1,0,3,2] row_mask:0xf bank_mask:0xf
	v_mov_b32_dpp v212, v204 quad_perm:[1,0,3,2] row_mask:0xf bank_mask:0xf
	v_mov_b32_dpp v213, v205 quad_perm:[1,0,3,2] row_mask:0xf bank_mask:0xf
	v_perm_b32 v231, v206, v198, v241
	v_add_f32_e32 v64, v64, v231
	v_add_f32_e32 v230, 0, v64
	v_perm_b32 v233, v206, v198, v242
	v_add_f32_e32 v60, v60, v233
	v_add_f32_e32 v230, v230, v60
	v_perm_b32 v231, v207, v199, v241
	v_add_f32_e32 v56, v56, v231
	v_add_f32_e32 v230, v230, v56
	v_perm_b32 v233, v207, v199, v242
	v_add_f32_e32 v52, v52, v233
	v_add_f32_e32 v230, v230, v52
	v_perm_b32 v231, v208, v200, v241
	v_add_f32_e32 v48, v48, v231
	v_add_f32_e32 v230, v230, v48
	v_perm_b32 v233, v208, v200, v242
	v_add_f32_e32 v44, v44, v233
	v_add_f32_e32 v230, v230, v44
	v_perm_b32 v231, v209, v201, v241
	v_add_f32_e32 v40, v40, v231
	v_add_f32_e32 v230, v230, v40
	v_perm_b32 v233, v209, v201, v242
	v_add_f32_e32 v36, v36, v233
	v_add_f32_e32 v230, v230, v36
	v_perm_b32 v231, v210, v202, v241
	v_add_f32_e32 v32, v32, v231
	v_add_f32_e32 v230, v230, v32
	v_perm_b32 v233, v210, v202, v242
	v_add_f32_e32 v28, v28, v233
	v_add_f32_e32 v230, v230, v28
	v_perm_b32 v231, v211, v203, v241
	v_add_f32_e32 v24, v24, v231
	v_add_f32_e32 v230, v230, v24
	v_perm_b32 v233, v211, v203, v242
	v_add_f32_e32 v20, v20, v233
	v_add_f32_e32 v230, v230, v20
	v_perm_b32 v231, v212, v204, v241
	v_add_f32_e32 v16, v16, v231
	v_add_f32_e32 v230, v230, v16
	v_perm_b32 v233, v212, v204, v242
	v_add_f32_e32 v12, v12, v233
	v_add_f32_e32 v230, v230, v12
	v_perm_b32 v231, v213, v205, v241
	v_add_f32_e32 v8, v8, v231
	v_add_f32_e32 v230, v230, v8
	v_perm_b32 v233, v213, v205, v242
	v_add_f32_e32 v4, v4, v233
	v_add_f32_e32 v230, v230, v4
	v_or_b32_e32 v116, 3, v112
	v_mov_b32_e32 v117, s11
	v_lshlrev_b64 v[114:115], 12, v[116:117]
	v_lshl_add_u64 v[114:115], s[78:79], 0, v[114:115]
	v_lshl_add_u64 v[114:115], v[114:115], 0, s[96:97]
	v_lshl_add_u64 v[114:115], v[114:115], 0, v[110:111]
	v_lshl_add_u64 v[114:115], v[114:115], 0, s[80:81]
	v_lshlrev_b64 v[118:119], 13, v[116:117]
	v_lshl_add_u64 v[118:119], s[92:93], 0, v[118:119]
	v_lshl_add_u64 v[118:119], v[118:119], 0, s[96:97]
	v_lshl_add_u64 v[118:119], v[118:119], 0, v[110:111]
	v_lshl_add_u64 v[118:119], v[118:119], 0, s[90:91]
	v_lshl_add_u64 v[114:115], v[114:115], 0, v[244:245]
	v_lshl_add_u64 v[118:119], v[118:119], 0, v[244:245]
	global_load_dword v198, v[114:115], off offset:0
	global_load_dword v199, v[114:115], off offset:64
	global_load_dword v200, v[114:115], off offset:128
	global_load_dword v201, v[114:115], off offset:192
	global_load_dword v202, v[114:115], off offset:256
	global_load_dword v203, v[114:115], off offset:320
	global_load_dword v204, v[114:115], off offset:384
	global_load_dword v205, v[114:115], off offset:448
	s_nop 1
	v_add_f32_dpp v230, v230, v230 row_ror:8 row_mask:0xf bank_mask:0xf bound_ctrl:1
	s_nop 1
	v_add_f32_dpp v230, v230, v230 row_ror:4 row_mask:0xf bank_mask:0xf bound_ctrl:1
	s_nop 1
	v_add_f32_dpp v230, v230, v230 row_ror:2 row_mask:0xf bank_mask:0xf bound_ctrl:1
	s_nop 1
	v_add_f32_dpp v230, v230, v230 row_ror:1 row_mask:0xf bank_mask:0xf bound_ctrl:1
	v_fmac_f32_e32 v60, 0xbb800000, v230
	v_mul_f32_e32 v231, v60, v60
	v_fmac_f32_e32 v64, 0xbb800000, v230
	v_fmac_f32_e32 v231, v64, v64
	v_fmac_f32_e32 v56, 0xbb800000, v230
	v_fmac_f32_e32 v231, v56, v56
	v_fmac_f32_e32 v52, 0xbb800000, v230
	v_fmac_f32_e32 v231, v52, v52
	v_fmac_f32_e32 v48, 0xbb800000, v230
	v_fmac_f32_e32 v231, v48, v48
	v_fmac_f32_e32 v44, 0xbb800000, v230
	v_fmac_f32_e32 v231, v44, v44
	v_fmac_f32_e32 v40, 0xbb800000, v230
	v_fmac_f32_e32 v231, v40, v40
	v_fmac_f32_e32 v36, 0xbb800000, v230
	v_fmac_f32_e32 v231, v36, v36
	v_fmac_f32_e32 v32, 0xbb800000, v230
	v_fmac_f32_e32 v231, v32, v32
	v_fmac_f32_e32 v28, 0xbb800000, v230
	v_fmac_f32_e32 v231, v28, v28
	v_fmac_f32_e32 v24, 0xbb800000, v230
	v_fmac_f32_e32 v231, v24, v24
	v_fmac_f32_e32 v20, 0xbb800000, v230
	v_fmac_f32_e32 v231, v20, v20
	v_fmac_f32_e32 v16, 0xbb800000, v230
	v_fmac_f32_e32 v231, v16, v16
	v_fmac_f32_e32 v12, 0xbb800000, v230
	v_fmac_f32_e32 v231, v12, v12
	v_fmac_f32_e32 v8, 0xbb800000, v230
	v_fmac_f32_e32 v231, v8, v8
	v_fmac_f32_e32 v4, 0xbb800000, v230
	v_fmac_f32_e32 v231, v4, v4
	s_nop 1
	v_add_f32_dpp v232, v231, v231 row_ror:8 row_mask:0xf bank_mask:0xf bound_ctrl:1
	s_nop 1
	v_add_f32_dpp v232, v232, v232 row_ror:4 row_mask:0xf bank_mask:0xf bound_ctrl:1
	s_nop 1
	v_add_f32_dpp v232, v232, v232 row_ror:2 row_mask:0xf bank_mask:0xf bound_ctrl:1
	s_nop 1
	v_add_f32_dpp v232, v232, v232 row_ror:1 row_mask:0xf bank_mask:0xf bound_ctrl:1
	v_fmamk_f32 v232, v232, 0x3b800000, v169
	v_cmp_gt_f32_e32 vcc, s7, v232
	v_mul_f32_e32 v233, 0x4f800000, v232
	s_nop 0
	v_cndmask_b32_e32 v232, v232, v233, vcc
	v_sqrt_f32_e32 v233, v232
	s_nop 0
	v_add_u32_e32 v234, -1, v233
	v_fma_f32 v235, -v234, v233, v232
	v_cmp_ge_f32_e64 s[0:1], 0, v235
	v_add_u32_e32 v235, 1, v233
	s_nop 0
	v_cndmask_b32_e64 v234, v233, v234, s[0:1]
	v_fma_f32 v233, -v235, v233, v232
	v_cmp_lt_f32_e64 s[0:1], 0, v233
	s_nop 1
	v_cndmask_b32_e64 v233, v234, v235, s[0:1]
	v_mul_f32_e32 v234, 0x37800000, v233
	s_nop 0
	v_cndmask_b32_e32 v233, v233, v234, vcc
	v_cmp_class_f32_e32 vcc, v232, v170
	s_nop 1
	v_cndmask_b32_e32 v232, v233, v232, vcc
	v_div_scale_f32 v233, s[0:1], v232, v232, 1.0
	v_rcp_f32_e32 v234, v233
	s_nop 0
	v_fma_f32 v235, -v233, v234, 1.0
	v_fmac_f32_e32 v234, v235, v234
	v_div_scale_f32 v235, vcc, 1.0, v232, 1.0
	v_mul_f32_e32 v236, v235, v234
	v_fma_f32 v237, -v233, v236, v235
	v_fmac_f32_e32 v236, v237, v234
	v_fma_f32 v233, -v233, v236, v235
	v_div_fmas_f32 v233, v233, v234, v236
	v_div_fixup_f32 v232, v233, v232, 1.0
	s_waitcnt vmcnt(8)
	v_mov_b32_dpp v222, v214 quad_perm:[1,0,3,2] row_mask:0xf bank_mask:0xf
	v_mov_b32_dpp v223, v215 quad_perm:[1,0,3,2] row_mask:0xf bank_mask:0xf
	v_mov_b32_dpp v224, v216 quad_perm:[1,0,3,2] row_mask:0xf bank_mask:0xf
	v_mov_b32_dpp v225, v217 quad_perm:[1,0,3,2] row_mask:0xf bank_mask:0xf
	v_mov_b32_dpp v226, v218 quad_perm:[1,0,3,2] row_mask:0xf bank_mask:0xf
	v_mov_b32_dpp v227, v219 quad_perm:[1,0,3,2] row_mask:0xf bank_mask:0xf
	v_mov_b32_dpp v228, v220 quad_perm:[1,0,3,2] row_mask:0xf bank_mask:0xf
	v_mov_b32_dpp v229, v221 quad_perm:[1,0,3,2] row_mask:0xf bank_mask:0xf
	v_perm_b32 v174, v222, v214, v241
	v_mul_f32_e32 v175, 0xbfb8aa3b, v174
	v_exp_f32_e32 v175, v175
	v_mul_f32_e32 v176, v64, v232
	v_mul_f32_e32 v176, v182, v176
	v_add_f32_e32 v175, 1.0, v175
	v_div_scale_f32 v177, s[0:1], v175, v175, 1.0
	v_rcp_f32_e32 v178, v177
	s_nop 0
	v_fma_f32 v179, -v177, v178, 1.0
	v_fmac_f32_e32 v178, v179, v178
	v_div_scale_f32 v179, vcc, 1.0, v175, 1.0
	v_mul_f32_e32 v180, v179, v178
	v_fma_f32 v181, -v177, v180, v179
	v_fmac_f32_e32 v180, v181, v178
	v_fma_f32 v177, -v177, v180, v179
	v_div_fmas_f32 v177, v177, v178, v180
	v_div_fixup_f32 v175, v177, v175, 1.0
	v_mul_f32_e32 v174, v175, v174
	v_mul_f32_e32 v174, v174, v176
	v_bfe_u32 v176, v174, 16, 1
	v_add3_u32 v174, v174, v176, s5
	v_perm_b32 v230, v222, v214, v242
	v_mul_f32_e32 v231, 0xbfb8aa3b, v230
	v_exp_f32_e32 v231, v231
	v_mul_f32_e32 v233, v60, v232
	v_mul_f32_e32 v233, v183, v233
	v_add_f32_e32 v231, 1.0, v231
	v_div_scale_f32 v234, s[0:1], v231, v231, 1.0
	v_rcp_f32_e32 v235, v234
	s_nop 0
	v_fma_f32 v236, -v234, v235, 1.0
	v_fmac_f32_e32 v235, v236, v235
	v_div_scale_f32 v236, vcc, 1.0, v231, 1.0
	v_mul_f32_e32 v237, v236, v235
	v_fma_f32 v109, -v234, v237, v236
	v_fmac_f32_e32 v237, v109, v235
	v_fma_f32 v234, -v234, v237, v236
	v_div_fmas_f32 v234, v234, v235, v237
	v_div_fixup_f32 v231, v234, v231, 1.0
	v_mul_f32_e32 v230, v231, v230
	v_mul_f32_e32 v230, v230, v233
	v_bfe_u32 v233, v230, 16, 1
	v_add3_u32 v230, v230, v233, s5
	v_bfi_b32 v246, v240, v174, v230
	v_bfi_b32 v248, v240, v230, v174
	s_nop 0
	v_mov_b32_dpp v247, v246 quad_perm:[1,0,3,2] row_mask:0xf bank_mask:0xf
	s_nop 0
	v_perm_b32 v248, v247, v248, v243
	global_store_dword v[120:121], v248, off offset:0
	v_perm_b32 v174, v223, v215, v241
	v_mul_f32_e32 v175, 0xbfb8aa3b, v174
	v_exp_f32_e32 v175, v175
	v_mul_f32_e32 v176, v56, v232
	v_mul_f32_e32 v176, v184, v176
	v_add_f32_e32 v175, 1.0, v175
	v_div_scale_f32 v177, s[0:1], v175, v175, 1.0
	v_rcp_f32_e32 v178, v177
	s_nop 0
	v_fma_f32 v179, -v177, v178, 1.0
	v_fmac_f32_e32 v178, v179, v178
	v_div_scale_f32 v179, vcc, 1.0, v175, 1.0
	v_mul_f32_e32 v180, v179, v178
	v_fma_f32 v181, -v177, v180, v179
	v_fmac_f32_e32 v180, v181, v178
	v_fma_f32 v177, -v177, v180, v179
	v_div_fmas_f32 v177, v177, v178, v180
	v_div_fixup_f32 v175, v177, v175, 1.0
	v_mul_f32_e32 v174, v175, v174
	v_mul_f32_e32 v174, v174, v176
	v_bfe_u32 v176, v174, 16, 1
	v_add3_u32 v174, v174, v176, s5
	v_perm_b32 v230, v223, v215, v242
	v_mul_f32_e32 v231, 0xbfb8aa3b, v230
	v_exp_f32_e32 v231, v231
	v_mul_f32_e32 v233, v52, v232
	v_mul_f32_e32 v233, v185, v233
	v_add_f32_e32 v231, 1.0, v231
	v_div_scale_f32 v234, s[0:1], v231, v231, 1.0
	v_rcp_f32_e32 v235, v234
	s_nop 0
	v_fma_f32 v236, -v234, v235, 1.0
	v_fmac_f32_e32 v235, v236, v235
	v_div_scale_f32 v236, vcc, 1.0, v231, 1.0
	v_mul_f32_e32 v237, v236, v235
	v_fma_f32 v109, -v234, v237, v236
	v_fmac_f32_e32 v237, v109, v235
	v_fma_f32 v234, -v234, v237, v236
	v_div_fmas_f32 v234, v234, v235, v237
	v_div_fixup_f32 v231, v234, v231, 1.0
	v_mul_f32_e32 v230, v231, v230
	v_mul_f32_e32 v230, v230, v233
	v_bfe_u32 v233, v230, 16, 1
	v_add3_u32 v230, v230, v233, s5
	v_bfi_b32 v246, v240, v174, v230
	v_bfi_b32 v248, v240, v230, v174
	s_nop 0
	v_mov_b32_dpp v247, v246 quad_perm:[1,0,3,2] row_mask:0xf bank_mask:0xf
	s_nop 0
	v_perm_b32 v248, v247, v248, v243
	global_store_dword v[120:121], v248, off offset:64
	v_perm_b32 v174, v224, v216, v241
	v_mul_f32_e32 v175, 0xbfb8aa3b, v174
	v_exp_f32_e32 v175, v175
	v_mul_f32_e32 v176, v48, v232
	v_mul_f32_e32 v176, v186, v176
	v_add_f32_e32 v175, 1.0, v175
	v_div_scale_f32 v177, s[0:1], v175, v175, 1.0
	v_rcp_f32_e32 v178, v177
	s_nop 0
	v_fma_f32 v179, -v177, v178, 1.0
	v_fmac_f32_e32 v178, v179, v178
	v_div_scale_f32 v179, vcc, 1.0, v175, 1.0
	v_mul_f32_e32 v180, v179, v178
	v_fma_f32 v181, -v177, v180, v179
	v_fmac_f32_e32 v180, v181, v178
	v_fma_f32 v177, -v177, v180, v179
	v_div_fmas_f32 v177, v177, v178, v180
	v_div_fixup_f32 v175, v177, v175, 1.0
	v_mul_f32_e32 v174, v175, v174
	v_mul_f32_e32 v174, v174, v176
	v_bfe_u32 v176, v174, 16, 1
	v_add3_u32 v174, v174, v176, s5
	v_perm_b32 v230, v224, v216, v242
	v_mul_f32_e32 v231, 0xbfb8aa3b, v230
	v_exp_f32_e32 v231, v231
	v_mul_f32_e32 v233, v44, v232
	v_mul_f32_e32 v233, v187, v233
	v_add_f32_e32 v231, 1.0, v231
	v_div_scale_f32 v234, s[0:1], v231, v231, 1.0
	v_rcp_f32_e32 v235, v234
	s_nop 0
	v_fma_f32 v236, -v234, v235, 1.0
	v_fmac_f32_e32 v235, v236, v235
	v_div_scale_f32 v236, vcc, 1.0, v231, 1.0
	v_mul_f32_e32 v237, v236, v235
	v_fma_f32 v109, -v234, v237, v236
	v_fmac_f32_e32 v237, v109, v235
	v_fma_f32 v234, -v234, v237, v236
	v_div_fmas_f32 v234, v234, v235, v237
	v_div_fixup_f32 v231, v234, v231, 1.0
	v_mul_f32_e32 v230, v231, v230
	v_mul_f32_e32 v230, v230, v233
	v_bfe_u32 v233, v230, 16, 1
	v_add3_u32 v230, v230, v233, s5
	v_bfi_b32 v246, v240, v174, v230
	v_bfi_b32 v248, v240, v230, v174
	s_nop 0
	v_mov_b32_dpp v247, v246 quad_perm:[1,0,3,2] row_mask:0xf bank_mask:0xf
	s_nop 0
	v_perm_b32 v248, v247, v248, v243
	global_store_dword v[120:121], v248, off offset:128
	v_perm_b32 v174, v225, v217, v241
	v_mul_f32_e32 v175, 0xbfb8aa3b, v174
	v_exp_f32_e32 v175, v175
	v_mul_f32_e32 v176, v40, v232
	v_mul_f32_e32 v176, v188, v176
	v_add_f32_e32 v175, 1.0, v175
	v_div_scale_f32 v177, s[0:1], v175, v175, 1.0
	v_rcp_f32_e32 v178, v177
	s_nop 0
	v_fma_f32 v179, -v177, v178, 1.0
	v_fmac_f32_e32 v178, v179, v178
	v_div_scale_f32 v179, vcc, 1.0, v175, 1.0
	v_mul_f32_e32 v180, v179, v178
	v_fma_f32 v181, -v177, v180, v179
	v_fmac_f32_e32 v180, v181, v178
	v_fma_f32 v177, -v177, v180, v179
	v_div_fmas_f32 v177, v177, v178, v180
	v_div_fixup_f32 v175, v177, v175, 1.0
	v_mul_f32_e32 v174, v175, v174
	v_mul_f32_e32 v174, v174, v176
	v_bfe_u32 v176, v174, 16, 1
	v_add3_u32 v174, v174, v176, s5
	v_perm_b32 v230, v225, v217, v242
	v_mul_f32_e32 v231, 0xbfb8aa3b, v230
	v_exp_f32_e32 v231, v231
	v_mul_f32_e32 v233, v36, v232
	v_mul_f32_e32 v233, v189, v233
	v_add_f32_e32 v231, 1.0, v231
	v_div_scale_f32 v234, s[0:1], v231, v231, 1.0
	v_rcp_f32_e32 v235, v234
	s_nop 0
	v_fma_f32 v236, -v234, v235, 1.0
	v_fmac_f32_e32 v235, v236, v235
	v_div_scale_f32 v236, vcc, 1.0, v231, 1.0
	v_mul_f32_e32 v237, v236, v235
	v_fma_f32 v109, -v234, v237, v236
	v_fmac_f32_e32 v237, v109, v235
	v_fma_f32 v234, -v234, v237, v236
	v_div_fmas_f32 v234, v234, v235, v237
	v_div_fixup_f32 v231, v234, v231, 1.0
	v_mul_f32_e32 v230, v231, v230
	v_mul_f32_e32 v230, v230, v233
	v_bfe_u32 v233, v230, 16, 1
	v_add3_u32 v230, v230, v233, s5
	v_bfi_b32 v246, v240, v174, v230
	v_bfi_b32 v248, v240, v230, v174
	s_nop 0
	v_mov_b32_dpp v247, v246 quad_perm:[1,0,3,2] row_mask:0xf bank_mask:0xf
	s_nop 0
	v_perm_b32 v248, v247, v248, v243
	global_store_dword v[120:121], v248, off offset:192
	v_perm_b32 v174, v226, v218, v241
	v_mul_f32_e32 v175, 0xbfb8aa3b, v174
	v_exp_f32_e32 v175, v175
	v_mul_f32_e32 v176, v32, v232
	v_mul_f32_e32 v176, v190, v176
	v_add_f32_e32 v175, 1.0, v175
	v_div_scale_f32 v177, s[0:1], v175, v175, 1.0
	v_rcp_f32_e32 v178, v177
	s_nop 0
	v_fma_f32 v179, -v177, v178, 1.0
	v_fmac_f32_e32 v178, v179, v178
	v_div_scale_f32 v179, vcc, 1.0, v175, 1.0
	v_mul_f32_e32 v180, v179, v178
	v_fma_f32 v181, -v177, v180, v179
	v_fmac_f32_e32 v180, v181, v178
	v_fma_f32 v177, -v177, v180, v179
	v_div_fmas_f32 v177, v177, v178, v180
	v_div_fixup_f32 v175, v177, v175, 1.0
	v_mul_f32_e32 v174, v175, v174
	v_mul_f32_e32 v174, v174, v176
	v_bfe_u32 v176, v174, 16, 1
	v_add3_u32 v174, v174, v176, s5
	v_perm_b32 v230, v226, v218, v242
	v_mul_f32_e32 v231, 0xbfb8aa3b, v230
	v_exp_f32_e32 v231, v231
	v_mul_f32_e32 v233, v28, v232
	v_mul_f32_e32 v233, v191, v233
	v_add_f32_e32 v231, 1.0, v231
	v_div_scale_f32 v234, s[0:1], v231, v231, 1.0
	v_rcp_f32_e32 v235, v234
	s_nop 0
	v_fma_f32 v236, -v234, v235, 1.0
	v_fmac_f32_e32 v235, v236, v235
	v_div_scale_f32 v236, vcc, 1.0, v231, 1.0
	v_mul_f32_e32 v237, v236, v235
	v_fma_f32 v109, -v234, v237, v236
	v_fmac_f32_e32 v237, v109, v235
	v_fma_f32 v234, -v234, v237, v236
	v_div_fmas_f32 v234, v234, v235, v237
	v_div_fixup_f32 v231, v234, v231, 1.0
	v_mul_f32_e32 v230, v231, v230
	v_mul_f32_e32 v230, v230, v233
	v_bfe_u32 v233, v230, 16, 1
	v_add3_u32 v230, v230, v233, s5
	v_bfi_b32 v246, v240, v174, v230
	v_bfi_b32 v248, v240, v230, v174
	s_nop 0
	v_mov_b32_dpp v247, v246 quad_perm:[1,0,3,2] row_mask:0xf bank_mask:0xf
	s_nop 0
	v_perm_b32 v248, v247, v248, v243
	global_store_dword v[120:121], v248, off offset:256
	v_perm_b32 v174, v227, v219, v241
	v_mul_f32_e32 v175, 0xbfb8aa3b, v174
	v_exp_f32_e32 v175, v175
	v_mul_f32_e32 v176, v24, v232
	v_mul_f32_e32 v176, v192, v176
	v_add_f32_e32 v175, 1.0, v175
	v_div_scale_f32 v177, s[0:1], v175, v175, 1.0
	v_rcp_f32_e32 v178, v177
	s_nop 0
	v_fma_f32 v179, -v177, v178, 1.0
	v_fmac_f32_e32 v178, v179, v178
	v_div_scale_f32 v179, vcc, 1.0, v175, 1.0
	v_mul_f32_e32 v180, v179, v178
	v_fma_f32 v181, -v177, v180, v179
	v_fmac_f32_e32 v180, v181, v178
	v_fma_f32 v177, -v177, v180, v179
	v_div_fmas_f32 v177, v177, v178, v180
	v_div_fixup_f32 v175, v177, v175, 1.0
	v_mul_f32_e32 v174, v175, v174
	v_mul_f32_e32 v174, v174, v176
	v_bfe_u32 v176, v174, 16, 1
	v_add3_u32 v174, v174, v176, s5
	v_perm_b32 v230, v227, v219, v242
	v_mul_f32_e32 v231, 0xbfb8aa3b, v230
	v_exp_f32_e32 v231, v231
	v_mul_f32_e32 v233, v20, v232
	v_mul_f32_e32 v233, v193, v233
	v_add_f32_e32 v231, 1.0, v231
	v_div_scale_f32 v234, s[0:1], v231, v231, 1.0
	v_rcp_f32_e32 v235, v234
	s_nop 0
	v_fma_f32 v236, -v234, v235, 1.0
	v_fmac_f32_e32 v235, v236, v235
	v_div_scale_f32 v236, vcc, 1.0, v231, 1.0
	v_mul_f32_e32 v237, v236, v235
	v_fma_f32 v109, -v234, v237, v236
	v_fmac_f32_e32 v237, v109, v235
	v_fma_f32 v234, -v234, v237, v236
	v_div_fmas_f32 v234, v234, v235, v237
	v_div_fixup_f32 v231, v234, v231, 1.0
	v_mul_f32_e32 v230, v231, v230
	v_mul_f32_e32 v230, v230, v233
	v_bfe_u32 v233, v230, 16, 1
	v_add3_u32 v230, v230, v233, s5
	v_bfi_b32 v246, v240, v174, v230
	v_bfi_b32 v248, v240, v230, v174
	s_nop 0
	v_mov_b32_dpp v247, v246 quad_perm:[1,0,3,2] row_mask:0xf bank_mask:0xf
	s_nop 0
	v_perm_b32 v248, v247, v248, v243
	global_store_dword v[120:121], v248, off offset:320
	v_perm_b32 v174, v228, v220, v241
	v_mul_f32_e32 v175, 0xbfb8aa3b, v174
	v_exp_f32_e32 v175, v175
	v_mul_f32_e32 v176, v16, v232
	v_mul_f32_e32 v176, v194, v176
	v_add_f32_e32 v175, 1.0, v175
	v_div_scale_f32 v177, s[0:1], v175, v175, 1.0
	v_rcp_f32_e32 v178, v177
	s_nop 0
	v_fma_f32 v179, -v177, v178, 1.0
	v_fmac_f32_e32 v178, v179, v178
	v_div_scale_f32 v179, vcc, 1.0, v175, 1.0
	v_mul_f32_e32 v180, v179, v178
	v_fma_f32 v181, -v177, v180, v179
	v_fmac_f32_e32 v180, v181, v178
	v_fma_f32 v177, -v177, v180, v179
	v_div_fmas_f32 v177, v177, v178, v180
	v_div_fixup_f32 v175, v177, v175, 1.0
	v_mul_f32_e32 v174, v175, v174
	v_mul_f32_e32 v174, v174, v176
	v_bfe_u32 v176, v174, 16, 1
	v_add3_u32 v174, v174, v176, s5
	v_perm_b32 v230, v228, v220, v242
	v_mul_f32_e32 v231, 0xbfb8aa3b, v230
	v_exp_f32_e32 v231, v231
	v_mul_f32_e32 v233, v12, v232
	v_mul_f32_e32 v233, v195, v233
	v_add_f32_e32 v231, 1.0, v231
	v_div_scale_f32 v234, s[0:1], v231, v231, 1.0
	v_rcp_f32_e32 v235, v234
	s_nop 0
	v_fma_f32 v236, -v234, v235, 1.0
	v_fmac_f32_e32 v235, v236, v235
	v_div_scale_f32 v236, vcc, 1.0, v231, 1.0
	v_mul_f32_e32 v237, v236, v235
	v_fma_f32 v109, -v234, v237, v236
	v_fmac_f32_e32 v237, v109, v235
	v_fma_f32 v234, -v234, v237, v236
	v_div_fmas_f32 v234, v234, v235, v237
	v_div_fixup_f32 v231, v234, v231, 1.0
	v_mul_f32_e32 v230, v231, v230
	v_mul_f32_e32 v230, v230, v233
	v_bfe_u32 v233, v230, 16, 1
	v_add3_u32 v230, v230, v233, s5
	v_bfi_b32 v246, v240, v174, v230
	v_bfi_b32 v248, v240, v230, v174
	s_nop 0
	v_mov_b32_dpp v247, v246 quad_perm:[1,0,3,2] row_mask:0xf bank_mask:0xf
	s_nop 0
	v_perm_b32 v248, v247, v248, v243
	global_store_dword v[120:121], v248, off offset:384
	v_perm_b32 v174, v229, v221, v241
	v_mul_f32_e32 v175, 0xbfb8aa3b, v174
	v_exp_f32_e32 v175, v175
	v_mul_f32_e32 v176, v8, v232
	v_mul_f32_e32 v176, v196, v176
	v_add_f32_e32 v175, 1.0, v175
	v_div_scale_f32 v177, s[0:1], v175, v175, 1.0
	v_rcp_f32_e32 v178, v177
	s_nop 0
	v_fma_f32 v179, -v177, v178, 1.0
	v_fmac_f32_e32 v178, v179, v178
	v_div_scale_f32 v179, vcc, 1.0, v175, 1.0
	v_mul_f32_e32 v180, v179, v178
	v_fma_f32 v181, -v177, v180, v179
	v_fmac_f32_e32 v180, v181, v178
	v_fma_f32 v177, -v177, v180, v179
	v_div_fmas_f32 v177, v177, v178, v180
	v_div_fixup_f32 v175, v177, v175, 1.0
	v_mul_f32_e32 v174, v175, v174
	v_mul_f32_e32 v174, v174, v176
	v_bfe_u32 v176, v174, 16, 1
	v_add3_u32 v174, v174, v176, s5
	v_perm_b32 v230, v229, v221, v242
	v_mul_f32_e32 v231, 0xbfb8aa3b, v230
	v_exp_f32_e32 v231, v231
	v_mul_f32_e32 v233, v4, v232
	v_mul_f32_e32 v233, v197, v233
	v_add_f32_e32 v231, 1.0, v231
	v_div_scale_f32 v234, s[0:1], v231, v231, 1.0
	v_rcp_f32_e32 v235, v234
	s_nop 0
	v_fma_f32 v236, -v234, v235, 1.0
	v_fmac_f32_e32 v235, v236, v235
	v_div_scale_f32 v236, vcc, 1.0, v231, 1.0
	v_mul_f32_e32 v237, v236, v235
	v_fma_f32 v109, -v234, v237, v236
	v_fmac_f32_e32 v237, v109, v235
	v_fma_f32 v234, -v234, v237, v236
	v_div_fmas_f32 v234, v234, v235, v237
	v_div_fixup_f32 v231, v234, v231, 1.0
	v_mul_f32_e32 v230, v231, v230
	v_mul_f32_e32 v230, v230, v233
	v_bfe_u32 v233, v230, 16, 1
	v_add3_u32 v230, v230, v233, s5
	v_bfi_b32 v246, v240, v174, v230
	v_bfi_b32 v248, v240, v230, v174
	s_nop 0
	v_mov_b32_dpp v247, v246 quad_perm:[1,0,3,2] row_mask:0xf bank_mask:0xf
	s_nop 0
	v_perm_b32 v248, v247, v248, v243
	global_store_dword v[120:121], v248, off offset:448
	global_load_dword v214, v[118:119], off offset:0
	global_load_dword v215, v[118:119], off offset:64
	global_load_dword v216, v[118:119], off offset:128
	global_load_dword v217, v[118:119], off offset:192
	global_load_dword v218, v[118:119], off offset:256
	global_load_dword v219, v[118:119], off offset:320
	global_load_dword v220, v[118:119], off offset:384
	global_load_dword v221, v[118:119], off offset:448
	v_mov_b32_e32 v120, v114
	v_mov_b32_e32 v121, v115
	s_waitcnt vmcnt(16)
	v_mov_b32_dpp v206, v198 quad_perm:[1,0,3,2] row_mask:0xf bank_mask:0xf
	v_mov_b32_dpp v207, v199 quad_perm:[1,0,3,2] row_mask:0xf bank_mask:0xf
	v_mov_b32_dpp v208, v200 quad_perm:[1,0,3,2] row_mask:0xf bank_mask:0xf
	v_mov_b32_dpp v209, v201 quad_perm:[1,0,3,2] row_mask:0xf bank_mask:0xf
	v_mov_b32_dpp v210, v202 quad_perm:[1,0,3,2] row_mask:0xf bank_mask:0xf
	v_mov_b32_dpp v211, v203 quad_perm:[1,0,3,2] row_mask:0xf bank_mask:0xf
	v_mov_b32_dpp v212, v204 quad_perm:[1,0,3,2] row_mask:0xf bank_mask:0xf
	v_mov_b32_dpp v213, v205 quad_perm:[1,0,3,2] row_mask:0xf bank_mask:0xf
	v_perm_b32 v231, v206, v198, v241
	v_add_f32_e32 v65, v65, v231
	v_add_f32_e32 v230, 0, v65
	v_perm_b32 v233, v206, v198, v242
	v_add_f32_e32 v61, v61, v233
	v_add_f32_e32 v230, v230, v61
	v_perm_b32 v231, v207, v199, v241
	v_add_f32_e32 v57, v57, v231
	v_add_f32_e32 v230, v230, v57
	v_perm_b32 v233, v207, v199, v242
	v_add_f32_e32 v53, v53, v233
	v_add_f32_e32 v230, v230, v53
	v_perm_b32 v231, v208, v200, v241
	v_add_f32_e32 v49, v49, v231
	v_add_f32_e32 v230, v230, v49
	v_perm_b32 v233, v208, v200, v242
	v_add_f32_e32 v45, v45, v233
	v_add_f32_e32 v230, v230, v45
	v_perm_b32 v231, v209, v201, v241
	v_add_f32_e32 v41, v41, v231
	v_add_f32_e32 v230, v230, v41
	v_perm_b32 v233, v209, v201, v242
	v_add_f32_e32 v37, v37, v233
	v_add_f32_e32 v230, v230, v37
	v_perm_b32 v231, v210, v202, v241
	v_add_f32_e32 v33, v33, v231
	v_add_f32_e32 v230, v230, v33
	v_perm_b32 v233, v210, v202, v242
	v_add_f32_e32 v29, v29, v233
	v_add_f32_e32 v230, v230, v29
	v_perm_b32 v231, v211, v203, v241
	v_add_f32_e32 v25, v25, v231
	v_add_f32_e32 v230, v230, v25
	v_perm_b32 v233, v211, v203, v242
	v_add_f32_e32 v21, v21, v233
	v_add_f32_e32 v230, v230, v21
	v_perm_b32 v231, v212, v204, v241
	v_add_f32_e32 v17, v17, v231
	v_add_f32_e32 v230, v230, v17
	v_perm_b32 v233, v212, v204, v242
	v_add_f32_e32 v13, v13, v233
	v_add_f32_e32 v230, v230, v13
	v_perm_b32 v231, v213, v205, v241
	v_add_f32_e32 v9, v9, v231
	v_add_f32_e32 v230, v230, v9
	v_perm_b32 v233, v213, v205, v242
	v_add_f32_e32 v5, v5, v233
	v_add_f32_e32 v230, v230, v5
	s_nop 1
	v_add_f32_dpp v230, v230, v230 row_ror:8 row_mask:0xf bank_mask:0xf bound_ctrl:1
	s_nop 1
	v_add_f32_dpp v230, v230, v230 row_ror:4 row_mask:0xf bank_mask:0xf bound_ctrl:1
	s_nop 1
	v_add_f32_dpp v230, v230, v230 row_ror:2 row_mask:0xf bank_mask:0xf bound_ctrl:1
	s_nop 1
	v_add_f32_dpp v230, v230, v230 row_ror:1 row_mask:0xf bank_mask:0xf bound_ctrl:1
	v_fmac_f32_e32 v61, 0xbb800000, v230
	v_mul_f32_e32 v231, v61, v61
	v_fmac_f32_e32 v65, 0xbb800000, v230
	v_fmac_f32_e32 v231, v65, v65
	v_fmac_f32_e32 v57, 0xbb800000, v230
	v_fmac_f32_e32 v231, v57, v57
	v_fmac_f32_e32 v53, 0xbb800000, v230
	v_fmac_f32_e32 v231, v53, v53
	v_fmac_f32_e32 v49, 0xbb800000, v230
	v_fmac_f32_e32 v231, v49, v49
	v_fmac_f32_e32 v45, 0xbb800000, v230
	v_fmac_f32_e32 v231, v45, v45
	v_fmac_f32_e32 v41, 0xbb800000, v230
	v_fmac_f32_e32 v231, v41, v41
	v_fmac_f32_e32 v37, 0xbb800000, v230
	v_fmac_f32_e32 v231, v37, v37
	v_fmac_f32_e32 v33, 0xbb800000, v230
	v_fmac_f32_e32 v231, v33, v33
	v_fmac_f32_e32 v29, 0xbb800000, v230
	v_fmac_f32_e32 v231, v29, v29
	v_fmac_f32_e32 v25, 0xbb800000, v230
	v_fmac_f32_e32 v231, v25, v25
	v_fmac_f32_e32 v21, 0xbb800000, v230
	v_fmac_f32_e32 v231, v21, v21
	v_fmac_f32_e32 v17, 0xbb800000, v230
	v_fmac_f32_e32 v231, v17, v17
	v_fmac_f32_e32 v13, 0xbb800000, v230
	v_fmac_f32_e32 v231, v13, v13
	v_fmac_f32_e32 v9, 0xbb800000, v230
	v_fmac_f32_e32 v231, v9, v9
	v_fmac_f32_e32 v5, 0xbb800000, v230
	v_fmac_f32_e32 v231, v5, v5
	s_nop 1
	v_add_f32_dpp v232, v231, v231 row_ror:8 row_mask:0xf bank_mask:0xf bound_ctrl:1
	s_nop 1
	v_add_f32_dpp v232, v232, v232 row_ror:4 row_mask:0xf bank_mask:0xf bound_ctrl:1
	s_nop 1
	v_add_f32_dpp v232, v232, v232 row_ror:2 row_mask:0xf bank_mask:0xf bound_ctrl:1
	s_nop 1
	v_add_f32_dpp v232, v232, v232 row_ror:1 row_mask:0xf bank_mask:0xf bound_ctrl:1
	v_fmamk_f32 v232, v232, 0x3b800000, v169
	v_cmp_gt_f32_e32 vcc, s7, v232
	v_mul_f32_e32 v233, 0x4f800000, v232
	s_nop 0
	v_cndmask_b32_e32 v232, v232, v233, vcc
	v_sqrt_f32_e32 v233, v232
	s_nop 0
	v_add_u32_e32 v234, -1, v233
	v_fma_f32 v235, -v234, v233, v232
	v_cmp_ge_f32_e64 s[0:1], 0, v235
	v_add_u32_e32 v235, 1, v233
	s_nop 0
	v_cndmask_b32_e64 v234, v233, v234, s[0:1]
	v_fma_f32 v233, -v235, v233, v232
	v_cmp_lt_f32_e64 s[0:1], 0, v233
	s_nop 1
	v_cndmask_b32_e64 v233, v234, v235, s[0:1]
	v_mul_f32_e32 v234, 0x37800000, v233
	s_nop 0
	v_cndmask_b32_e32 v233, v233, v234, vcc
	v_cmp_class_f32_e32 vcc, v232, v170
	s_nop 1
	v_cndmask_b32_e32 v232, v233, v232, vcc
	v_div_scale_f32 v233, s[0:1], v232, v232, 1.0
	v_rcp_f32_e32 v234, v233
	s_nop 0
	v_fma_f32 v235, -v233, v234, 1.0
	v_fmac_f32_e32 v234, v235, v234
	v_div_scale_f32 v235, vcc, 1.0, v232, 1.0
	v_mul_f32_e32 v236, v235, v234
	v_fma_f32 v237, -v233, v236, v235
	v_fmac_f32_e32 v236, v237, v234
	v_fma_f32 v233, -v233, v236, v235
	v_div_fmas_f32 v233, v233, v234, v236
	v_div_fixup_f32 v232, v233, v232, 1.0
	s_waitcnt vmcnt(0)
	v_mov_b32_dpp v222, v214 quad_perm:[1,0,3,2] row_mask:0xf bank_mask:0xf
	v_mov_b32_dpp v223, v215 quad_perm:[1,0,3,2] row_mask:0xf bank_mask:0xf
	v_mov_b32_dpp v224, v216 quad_perm:[1,0,3,2] row_mask:0xf bank_mask:0xf
	v_mov_b32_dpp v225, v217 quad_perm:[1,0,3,2] row_mask:0xf bank_mask:0xf
	v_mov_b32_dpp v226, v218 quad_perm:[1,0,3,2] row_mask:0xf bank_mask:0xf
	v_mov_b32_dpp v227, v219 quad_perm:[1,0,3,2] row_mask:0xf bank_mask:0xf
	v_mov_b32_dpp v228, v220 quad_perm:[1,0,3,2] row_mask:0xf bank_mask:0xf
	v_mov_b32_dpp v229, v221 quad_perm:[1,0,3,2] row_mask:0xf bank_mask:0xf
	v_perm_b32 v174, v222, v214, v241
	v_mul_f32_e32 v175, 0xbfb8aa3b, v174
	v_exp_f32_e32 v175, v175
	v_mul_f32_e32 v176, v65, v232
	v_mul_f32_e32 v176, v182, v176
	v_add_f32_e32 v175, 1.0, v175
	v_div_scale_f32 v177, s[0:1], v175, v175, 1.0
	v_rcp_f32_e32 v178, v177
	s_nop 0
	v_fma_f32 v179, -v177, v178, 1.0
	v_fmac_f32_e32 v178, v179, v178
	v_div_scale_f32 v179, vcc, 1.0, v175, 1.0
	v_mul_f32_e32 v180, v179, v178
	v_fma_f32 v181, -v177, v180, v179
	v_fmac_f32_e32 v180, v181, v178
	v_fma_f32 v177, -v177, v180, v179
	v_div_fmas_f32 v177, v177, v178, v180
	v_div_fixup_f32 v175, v177, v175, 1.0
	v_mul_f32_e32 v174, v175, v174
	v_mul_f32_e32 v174, v174, v176
	v_bfe_u32 v176, v174, 16, 1
	v_add3_u32 v174, v174, v176, s5
	v_perm_b32 v230, v222, v214, v242
	v_mul_f32_e32 v231, 0xbfb8aa3b, v230
	v_exp_f32_e32 v231, v231
	v_mul_f32_e32 v233, v61, v232
	v_mul_f32_e32 v233, v183, v233
	v_add_f32_e32 v231, 1.0, v231
	v_div_scale_f32 v234, s[0:1], v231, v231, 1.0
	v_rcp_f32_e32 v235, v234
	s_nop 0
	v_fma_f32 v236, -v234, v235, 1.0
	v_fmac_f32_e32 v235, v236, v235
	v_div_scale_f32 v236, vcc, 1.0, v231, 1.0
	v_mul_f32_e32 v237, v236, v235
	v_fma_f32 v109, -v234, v237, v236
	v_fmac_f32_e32 v237, v109, v235
	v_fma_f32 v234, -v234, v237, v236
	v_div_fmas_f32 v234, v234, v235, v237
	v_div_fixup_f32 v231, v234, v231, 1.0
	v_mul_f32_e32 v230, v231, v230
	v_mul_f32_e32 v230, v230, v233
	v_bfe_u32 v233, v230, 16, 1
	v_add3_u32 v230, v230, v233, s5
	v_bfi_b32 v246, v240, v174, v230
	v_bfi_b32 v248, v240, v230, v174
	s_nop 0
	v_mov_b32_dpp v247, v246 quad_perm:[1,0,3,2] row_mask:0xf bank_mask:0xf
	s_nop 0
	v_perm_b32 v248, v247, v248, v243
	global_store_dword v[120:121], v248, off offset:0
	v_perm_b32 v174, v223, v215, v241
	v_mul_f32_e32 v175, 0xbfb8aa3b, v174
	v_exp_f32_e32 v175, v175
	v_mul_f32_e32 v176, v57, v232
	v_mul_f32_e32 v176, v184, v176
	v_add_f32_e32 v175, 1.0, v175
	v_div_scale_f32 v177, s[0:1], v175, v175, 1.0
	v_rcp_f32_e32 v178, v177
	s_nop 0
	v_fma_f32 v179, -v177, v178, 1.0
	v_fmac_f32_e32 v178, v179, v178
	v_div_scale_f32 v179, vcc, 1.0, v175, 1.0
	v_mul_f32_e32 v180, v179, v178
	v_fma_f32 v181, -v177, v180, v179
	v_fmac_f32_e32 v180, v181, v178
	v_fma_f32 v177, -v177, v180, v179
	v_div_fmas_f32 v177, v177, v178, v180
	v_div_fixup_f32 v175, v177, v175, 1.0
	v_mul_f32_e32 v174, v175, v174
	v_mul_f32_e32 v174, v174, v176
	v_bfe_u32 v176, v174, 16, 1
	v_add3_u32 v174, v174, v176, s5
	v_perm_b32 v230, v223, v215, v242
	v_mul_f32_e32 v231, 0xbfb8aa3b, v230
	v_exp_f32_e32 v231, v231
	v_mul_f32_e32 v233, v53, v232
	v_mul_f32_e32 v233, v185, v233
	v_add_f32_e32 v231, 1.0, v231
	v_div_scale_f32 v234, s[0:1], v231, v231, 1.0
	v_rcp_f32_e32 v235, v234
	s_nop 0
	v_fma_f32 v236, -v234, v235, 1.0
	v_fmac_f32_e32 v235, v236, v235
	v_div_scale_f32 v236, vcc, 1.0, v231, 1.0
	v_mul_f32_e32 v237, v236, v235
	v_fma_f32 v109, -v234, v237, v236
	v_fmac_f32_e32 v237, v109, v235
	v_fma_f32 v234, -v234, v237, v236
	v_div_fmas_f32 v234, v234, v235, v237
	v_div_fixup_f32 v231, v234, v231, 1.0
	v_mul_f32_e32 v230, v231, v230
	v_mul_f32_e32 v230, v230, v233
	v_bfe_u32 v233, v230, 16, 1
	v_add3_u32 v230, v230, v233, s5
	v_bfi_b32 v246, v240, v174, v230
	v_bfi_b32 v248, v240, v230, v174
	s_nop 0
	v_mov_b32_dpp v247, v246 quad_perm:[1,0,3,2] row_mask:0xf bank_mask:0xf
	s_nop 0
	v_perm_b32 v248, v247, v248, v243
	global_store_dword v[120:121], v248, off offset:64
	v_perm_b32 v174, v224, v216, v241
	v_mul_f32_e32 v175, 0xbfb8aa3b, v174
	v_exp_f32_e32 v175, v175
	v_mul_f32_e32 v176, v49, v232
	v_mul_f32_e32 v176, v186, v176
	v_add_f32_e32 v175, 1.0, v175
	v_div_scale_f32 v177, s[0:1], v175, v175, 1.0
	v_rcp_f32_e32 v178, v177
	s_nop 0
	v_fma_f32 v179, -v177, v178, 1.0
	v_fmac_f32_e32 v178, v179, v178
	v_div_scale_f32 v179, vcc, 1.0, v175, 1.0
	v_mul_f32_e32 v180, v179, v178
	v_fma_f32 v181, -v177, v180, v179
	v_fmac_f32_e32 v180, v181, v178
	v_fma_f32 v177, -v177, v180, v179
	v_div_fmas_f32 v177, v177, v178, v180
	v_div_fixup_f32 v175, v177, v175, 1.0
	v_mul_f32_e32 v174, v175, v174
	v_mul_f32_e32 v174, v174, v176
	v_bfe_u32 v176, v174, 16, 1
	v_add3_u32 v174, v174, v176, s5
	v_perm_b32 v230, v224, v216, v242
	v_mul_f32_e32 v231, 0xbfb8aa3b, v230
	v_exp_f32_e32 v231, v231
	v_mul_f32_e32 v233, v45, v232
	v_mul_f32_e32 v233, v187, v233
	v_add_f32_e32 v231, 1.0, v231
	v_div_scale_f32 v234, s[0:1], v231, v231, 1.0
	v_rcp_f32_e32 v235, v234
	s_nop 0
	v_fma_f32 v236, -v234, v235, 1.0
	v_fmac_f32_e32 v235, v236, v235
	v_div_scale_f32 v236, vcc, 1.0, v231, 1.0
	v_mul_f32_e32 v237, v236, v235
	v_fma_f32 v109, -v234, v237, v236
	v_fmac_f32_e32 v237, v109, v235
	v_fma_f32 v234, -v234, v237, v236
	v_div_fmas_f32 v234, v234, v235, v237
	v_div_fixup_f32 v231, v234, v231, 1.0
	v_mul_f32_e32 v230, v231, v230
	v_mul_f32_e32 v230, v230, v233
	v_bfe_u32 v233, v230, 16, 1
	v_add3_u32 v230, v230, v233, s5
	v_bfi_b32 v246, v240, v174, v230
	v_bfi_b32 v248, v240, v230, v174
	s_nop 0
	v_mov_b32_dpp v247, v246 quad_perm:[1,0,3,2] row_mask:0xf bank_mask:0xf
	s_nop 0
	v_perm_b32 v248, v247, v248, v243
	global_store_dword v[120:121], v248, off offset:128
	v_perm_b32 v174, v225, v217, v241
	v_mul_f32_e32 v175, 0xbfb8aa3b, v174
	v_exp_f32_e32 v175, v175
	v_mul_f32_e32 v176, v41, v232
	v_mul_f32_e32 v176, v188, v176
	v_add_f32_e32 v175, 1.0, v175
	v_div_scale_f32 v177, s[0:1], v175, v175, 1.0
	v_rcp_f32_e32 v178, v177
	s_nop 0
	v_fma_f32 v179, -v177, v178, 1.0
	v_fmac_f32_e32 v178, v179, v178
	v_div_scale_f32 v179, vcc, 1.0, v175, 1.0
	v_mul_f32_e32 v180, v179, v178
	v_fma_f32 v181, -v177, v180, v179
	v_fmac_f32_e32 v180, v181, v178
	v_fma_f32 v177, -v177, v180, v179
	v_div_fmas_f32 v177, v177, v178, v180
	v_div_fixup_f32 v175, v177, v175, 1.0
	v_mul_f32_e32 v174, v175, v174
	v_mul_f32_e32 v174, v174, v176
	v_bfe_u32 v176, v174, 16, 1
	v_add3_u32 v174, v174, v176, s5
	v_perm_b32 v230, v225, v217, v242
	v_mul_f32_e32 v231, 0xbfb8aa3b, v230
	v_exp_f32_e32 v231, v231
	v_mul_f32_e32 v233, v37, v232
	v_mul_f32_e32 v233, v189, v233
	v_add_f32_e32 v231, 1.0, v231
	v_div_scale_f32 v234, s[0:1], v231, v231, 1.0
	v_rcp_f32_e32 v235, v234
	s_nop 0
	v_fma_f32 v236, -v234, v235, 1.0
	v_fmac_f32_e32 v235, v236, v235
	v_div_scale_f32 v236, vcc, 1.0, v231, 1.0
	v_mul_f32_e32 v237, v236, v235
	v_fma_f32 v109, -v234, v237, v236
	v_fmac_f32_e32 v237, v109, v235
	v_fma_f32 v234, -v234, v237, v236
	v_div_fmas_f32 v234, v234, v235, v237
	v_div_fixup_f32 v231, v234, v231, 1.0
	v_mul_f32_e32 v230, v231, v230
	v_mul_f32_e32 v230, v230, v233
	v_bfe_u32 v233, v230, 16, 1
	v_add3_u32 v230, v230, v233, s5
	v_bfi_b32 v246, v240, v174, v230
	v_bfi_b32 v248, v240, v230, v174
	s_nop 0
	v_mov_b32_dpp v247, v246 quad_perm:[1,0,3,2] row_mask:0xf bank_mask:0xf
	s_nop 0
	v_perm_b32 v248, v247, v248, v243
	global_store_dword v[120:121], v248, off offset:192
	v_perm_b32 v174, v226, v218, v241
	v_mul_f32_e32 v175, 0xbfb8aa3b, v174
	v_exp_f32_e32 v175, v175
	v_mul_f32_e32 v176, v33, v232
	v_mul_f32_e32 v176, v190, v176
	v_add_f32_e32 v175, 1.0, v175
	v_div_scale_f32 v177, s[0:1], v175, v175, 1.0
	v_rcp_f32_e32 v178, v177
	s_nop 0
	v_fma_f32 v179, -v177, v178, 1.0
	v_fmac_f32_e32 v178, v179, v178
	v_div_scale_f32 v179, vcc, 1.0, v175, 1.0
	v_mul_f32_e32 v180, v179, v178
	v_fma_f32 v181, -v177, v180, v179
	v_fmac_f32_e32 v180, v181, v178
	v_fma_f32 v177, -v177, v180, v179
	v_div_fmas_f32 v177, v177, v178, v180
	v_div_fixup_f32 v175, v177, v175, 1.0
	v_mul_f32_e32 v174, v175, v174
	v_mul_f32_e32 v174, v174, v176
	v_bfe_u32 v176, v174, 16, 1
	v_add3_u32 v174, v174, v176, s5
	v_perm_b32 v230, v226, v218, v242
	v_mul_f32_e32 v231, 0xbfb8aa3b, v230
	v_exp_f32_e32 v231, v231
	v_mul_f32_e32 v233, v29, v232
	v_mul_f32_e32 v233, v191, v233
	v_add_f32_e32 v231, 1.0, v231
	v_div_scale_f32 v234, s[0:1], v231, v231, 1.0
	v_rcp_f32_e32 v235, v234
	s_nop 0
	v_fma_f32 v236, -v234, v235, 1.0
	v_fmac_f32_e32 v235, v236, v235
	v_div_scale_f32 v236, vcc, 1.0, v231, 1.0
	v_mul_f32_e32 v237, v236, v235
	v_fma_f32 v109, -v234, v237, v236
	v_fmac_f32_e32 v237, v109, v235
	v_fma_f32 v234, -v234, v237, v236
	v_div_fmas_f32 v234, v234, v235, v237
	v_div_fixup_f32 v231, v234, v231, 1.0
	v_mul_f32_e32 v230, v231, v230
	v_mul_f32_e32 v230, v230, v233
	v_bfe_u32 v233, v230, 16, 1
	v_add3_u32 v230, v230, v233, s5
	v_bfi_b32 v246, v240, v174, v230
	v_bfi_b32 v248, v240, v230, v174
	s_nop 0
	v_mov_b32_dpp v247, v246 quad_perm:[1,0,3,2] row_mask:0xf bank_mask:0xf
	s_nop 0
	v_perm_b32 v248, v247, v248, v243
	global_store_dword v[120:121], v248, off offset:256
	v_perm_b32 v174, v227, v219, v241
	v_mul_f32_e32 v175, 0xbfb8aa3b, v174
	v_exp_f32_e32 v175, v175
	v_mul_f32_e32 v176, v25, v232
	v_mul_f32_e32 v176, v192, v176
	v_add_f32_e32 v175, 1.0, v175
	v_div_scale_f32 v177, s[0:1], v175, v175, 1.0
	v_rcp_f32_e32 v178, v177
	s_nop 0
	v_fma_f32 v179, -v177, v178, 1.0
	v_fmac_f32_e32 v178, v179, v178
	v_div_scale_f32 v179, vcc, 1.0, v175, 1.0
	v_mul_f32_e32 v180, v179, v178
	v_fma_f32 v181, -v177, v180, v179
	v_fmac_f32_e32 v180, v181, v178
	v_fma_f32 v177, -v177, v180, v179
	v_div_fmas_f32 v177, v177, v178, v180
	v_div_fixup_f32 v175, v177, v175, 1.0
	v_mul_f32_e32 v174, v175, v174
	v_mul_f32_e32 v174, v174, v176
	v_bfe_u32 v176, v174, 16, 1
	v_add3_u32 v174, v174, v176, s5
	v_perm_b32 v230, v227, v219, v242
	v_mul_f32_e32 v231, 0xbfb8aa3b, v230
	v_exp_f32_e32 v231, v231
	v_mul_f32_e32 v233, v21, v232
	v_mul_f32_e32 v233, v193, v233
	v_add_f32_e32 v231, 1.0, v231
	v_div_scale_f32 v234, s[0:1], v231, v231, 1.0
	v_rcp_f32_e32 v235, v234
	s_nop 0
	v_fma_f32 v236, -v234, v235, 1.0
	v_fmac_f32_e32 v235, v236, v235
	v_div_scale_f32 v236, vcc, 1.0, v231, 1.0
	v_mul_f32_e32 v237, v236, v235
	v_fma_f32 v109, -v234, v237, v236
	v_fmac_f32_e32 v237, v109, v235
	v_fma_f32 v234, -v234, v237, v236
	v_div_fmas_f32 v234, v234, v235, v237
	v_div_fixup_f32 v231, v234, v231, 1.0
	v_mul_f32_e32 v230, v231, v230
	v_mul_f32_e32 v230, v230, v233
	v_bfe_u32 v233, v230, 16, 1
	v_add3_u32 v230, v230, v233, s5
	v_bfi_b32 v246, v240, v174, v230
	v_bfi_b32 v248, v240, v230, v174
	s_nop 0
	v_mov_b32_dpp v247, v246 quad_perm:[1,0,3,2] row_mask:0xf bank_mask:0xf
	s_nop 0
	v_perm_b32 v248, v247, v248, v243
	global_store_dword v[120:121], v248, off offset:320
	v_perm_b32 v174, v228, v220, v241
	v_mul_f32_e32 v175, 0xbfb8aa3b, v174
	v_exp_f32_e32 v175, v175
	v_mul_f32_e32 v176, v17, v232
	v_mul_f32_e32 v176, v194, v176
	v_add_f32_e32 v175, 1.0, v175
	v_div_scale_f32 v177, s[0:1], v175, v175, 1.0
	v_rcp_f32_e32 v178, v177
	s_nop 0
	v_fma_f32 v179, -v177, v178, 1.0
	v_fmac_f32_e32 v178, v179, v178
	v_div_scale_f32 v179, vcc, 1.0, v175, 1.0
	v_mul_f32_e32 v180, v179, v178
	v_fma_f32 v181, -v177, v180, v179
	v_fmac_f32_e32 v180, v181, v178
	v_fma_f32 v177, -v177, v180, v179
	v_div_fmas_f32 v177, v177, v178, v180
	v_div_fixup_f32 v175, v177, v175, 1.0
	v_mul_f32_e32 v174, v175, v174
	v_mul_f32_e32 v174, v174, v176
	v_bfe_u32 v176, v174, 16, 1
	v_add3_u32 v174, v174, v176, s5
	v_perm_b32 v230, v228, v220, v242
	v_mul_f32_e32 v231, 0xbfb8aa3b, v230
	v_exp_f32_e32 v231, v231
	v_mul_f32_e32 v233, v13, v232
	v_mul_f32_e32 v233, v195, v233
	v_add_f32_e32 v231, 1.0, v231
	v_div_scale_f32 v234, s[0:1], v231, v231, 1.0
	v_rcp_f32_e32 v235, v234
	s_nop 0
	v_fma_f32 v236, -v234, v235, 1.0
	v_fmac_f32_e32 v235, v236, v235
	v_div_scale_f32 v236, vcc, 1.0, v231, 1.0
	v_mul_f32_e32 v237, v236, v235
	v_fma_f32 v109, -v234, v237, v236
	v_fmac_f32_e32 v237, v109, v235
	v_fma_f32 v234, -v234, v237, v236
	v_div_fmas_f32 v234, v234, v235, v237
	v_div_fixup_f32 v231, v234, v231, 1.0
	v_mul_f32_e32 v230, v231, v230
	v_mul_f32_e32 v230, v230, v233
	v_bfe_u32 v233, v230, 16, 1
	v_add3_u32 v230, v230, v233, s5
	v_bfi_b32 v246, v240, v174, v230
	v_bfi_b32 v248, v240, v230, v174
	s_nop 0
	v_mov_b32_dpp v247, v246 quad_perm:[1,0,3,2] row_mask:0xf bank_mask:0xf
	s_nop 0
	v_perm_b32 v248, v247, v248, v243
	global_store_dword v[120:121], v248, off offset:384
	v_perm_b32 v174, v229, v221, v241
	v_mul_f32_e32 v175, 0xbfb8aa3b, v174
	v_exp_f32_e32 v175, v175
	v_mul_f32_e32 v176, v9, v232
	v_mul_f32_e32 v176, v196, v176
	v_add_f32_e32 v175, 1.0, v175
	v_div_scale_f32 v177, s[0:1], v175, v175, 1.0
	v_rcp_f32_e32 v178, v177
	s_nop 0
	v_fma_f32 v179, -v177, v178, 1.0
	v_fmac_f32_e32 v178, v179, v178
	v_div_scale_f32 v179, vcc, 1.0, v175, 1.0
	v_mul_f32_e32 v180, v179, v178
	v_fma_f32 v181, -v177, v180, v179
	v_fmac_f32_e32 v180, v181, v178
	v_fma_f32 v177, -v177, v180, v179
	v_div_fmas_f32 v177, v177, v178, v180
	v_div_fixup_f32 v175, v177, v175, 1.0
	v_mul_f32_e32 v174, v175, v174
	v_mul_f32_e32 v174, v174, v176
	v_bfe_u32 v176, v174, 16, 1
	v_add3_u32 v174, v174, v176, s5
	v_perm_b32 v230, v229, v221, v242
	v_mul_f32_e32 v231, 0xbfb8aa3b, v230
	v_exp_f32_e32 v231, v231
	v_mul_f32_e32 v233, v5, v232
	v_mul_f32_e32 v233, v197, v233
	v_add_f32_e32 v231, 1.0, v231
	v_div_scale_f32 v234, s[0:1], v231, v231, 1.0
	v_rcp_f32_e32 v235, v234
	s_nop 0
	v_fma_f32 v236, -v234, v235, 1.0
	v_fmac_f32_e32 v235, v236, v235
	v_div_scale_f32 v236, vcc, 1.0, v231, 1.0
	v_mul_f32_e32 v237, v236, v235
	v_fma_f32 v109, -v234, v237, v236
	v_fmac_f32_e32 v237, v109, v235
	v_fma_f32 v234, -v234, v237, v236
	v_div_fmas_f32 v234, v234, v235, v237
	v_div_fixup_f32 v231, v234, v231, 1.0
	v_mul_f32_e32 v230, v231, v230
	v_mul_f32_e32 v230, v230, v233
	v_bfe_u32 v233, v230, 16, 1
	v_add3_u32 v230, v230, v233, s5
	v_bfi_b32 v246, v240, v174, v230
	v_bfi_b32 v248, v240, v230, v174
	s_nop 0
	v_mov_b32_dpp v247, v246 quad_perm:[1,0,3,2] row_mask:0xf bank_mask:0xf
	s_nop 0
	v_perm_b32 v248, v247, v248, v243
	global_store_dword v[120:121], v248, off offset:448
	s_cmpk_lt_i32 s3, 0x380
	s_barrier
	s_cbranch_scc0 .LBB0_699
